# six norm loops: loop-invariant gain/scale/shift loads consolidated per iteration + next-rows L2 touch
# speedup vs baseline: 1.0056x; 1.0042x over previous
; template <bool ZP, bool XF32, bool OUT8 = false>
; __device__ __forceinline__ void norm_phase(LAS unsigned char* lds, const void* xin, const float* gain, const float* sh, const float* sc, bf16* hout, const float* wzt, float* zout, int lane, int wave, int vcu, int G) {
;     ...
;     for (int it_ = 0; it_ < nit; ++it_) {
;         const int m0 = xdeal ? 2048 * (gw >> 8) + 2 * (gw & 255) + 512 * it_ : 2 * gw + it_ * 2 * NGW;
;         if (m0 >= M) break;
.LBB0_679:
	s_mov_b64 s[100:101], 0x200000
	s_and_b64 vcc, exec, s[4:5]
	s_mov_b32 s14, s23
	s_cbranch_vccz .LBB0_681
	s_cmpk_gt_i32 s14, 0x3fff
	s_mov_b64 s[8:9], -1
	s_cbranch_scc1 .LBB0_678
	s_branch .LBB0_682

; __device__ __forceinline__ void unpack8(const v4u& w, float (&f)[8]) { f[0] = bflo(w.x); f[1] = bfhi(w.x); f[2] = bflo(w.y); f[3] = bfhi(w.y); f[4] = bflo(w.z); f[5] = bfhi(w.z); f[6] = bflo(w.w); f[7] = bfhi(w.w); }
; template <bool ZP, bool XF32, bool OUT8 = false>
; __device__ __forceinline__ void norm_phase(LAS unsigned char* lds, const void* xin, const float* gain, const float* sh, const float* sc, bf16* hout, const float* wzt, float* zout, int lane, int wave, int vcu, int G) {
;     ...
;     for (int it_ = 0; it_ < nit; ++it_) {
;         const int m0 = xdeal ? 2048 * (gw >> 8) + 2 * (gw & 255) + 512 * it_ : 2 * gw + it_ * 2 * NGW;
;         if (m0 >= M) break;
;         f32x4 v[2][4][2]; float ss[2] = {0.f, 0.f};
; #pragma unroll
;         for (int r = 0; r < 2; ++r)
; #pragma unroll
;             for (int j = 0; j < 4; ++j) {
;                 if constexpr (XF32) { const float* xr = (const float*)xin + (size_t)(m0 + r) * D + 8 * lane; v[r][j][0] = *(const f32x4*)(xr + 512 * j); v[r][j][1] = *(const f32x4*)(xr + 512 * j + 4); }
;                 else { float f[8]; unpack8(*(const v4u*)((const bf16*)xin + (size_t)(m0 + r) * D + 8 * lane + 512 * j), f); v[r][j][0] = (f32x4){f[0], f[1], f[2], f[3]}; v[r][j][1] = (f32x4){f[4], f[5], f[6], f[7]}; } }
; #pragma unroll
;         for (int r = 0; r < 2; ++r)
; #pragma unroll
;             for (int j = 0; j < 4; ++j)
; #pragma unroll
;                 for (int e = 0; e < 4; ++e) ss[r] += v[r][j][0][e] * v[r][j][0][e] + v[r][j][1][e] * v[r][j][1][e];
; #pragma unroll
;         for (int r = 0; r < 2; ++r) { const int m = m0 + r, b = m >> 11;
;             const float rstd = rsqrtf(wave_sum(ss[r]) * (1.0f / D) + EPS);
; #pragma unroll
;             for (int j = 0; j < 4; ++j) { const int col = 512 * j + 8 * lane;
; #pragma unroll
;                 for (int q = 0; q < 2; ++q) { const f32x4 gg = *(const f32x4*)(gain + col + 4 * q), s1 = *(const f32x4*)(sc + (size_t)b * MODW + col + 4 * q), s0 = *(const f32x4*)(sh + (size_t)b * MODW + col + 4 * q);
;                     v[r][j][q] = (v[r][j][q] * rstd * gg) * (s1 + 1.0f) + s0; }
.LBB0_682:
	s_ashr_i32 s15, s14, 31
	s_add_i32 s10, s14, 1
	s_lshl_b64 s[12:13], s[14:15], 12
	s_ashr_i32 s11, s10, 31
	v_lshl_add_u64 v[2:3], v[6:7], 0, s[12:13]
	v_lshl_add_u64 v[244:245], v[2:3], 0, s[100:101]
	s_lshl_b64 s[8:9], s[10:11], 12
	global_load_dwordx4 v[18:21], v[2:3], off offset:1024
	global_load_dwordx4 v[22:25], v[2:3], off offset:3072
	global_load_dwordx4 v[32:35], v[2:3], off
	global_load_dwordx4 v[38:41], v[2:3], off offset:2048
	v_lshl_add_u64 v[26:27], v[6:7], 0, s[8:9]
	v_lshl_add_u64 v[246:247], v[26:27], 0, s[100:101]
	global_load_dwordx4 v[78:81], v[26:27], off offset:1024
	global_load_dwordx4 v[92:95], v[26:27], off
	global_load_dwordx4 v[2:5], v[26:27], off offset:3072
	global_load_dwordx4 v[96:99], v[26:27], off offset:2048
	s_ashr_i32 s0, s14, 11
	s_mul_hi_i32 s1, s0, 0xc000
	s_mul_i32 s0, s0, 0xc000
	s_add_u32 s14, s19, s0
	s_addc_u32 s15, s20, s1
	s_add_u32 s16, s7, s0
	s_addc_u32 s17, s18, s1
	v_cmp_lt_i32_e32 vcc, v86, v85
	s_ashr_i32 s0, s10, 11
	s_mul_hi_i32 s1, s0, 0xc000
	v_cndmask_b32_e32 v82, v84, v86, vcc
	v_lshlrev_b32_e32 v82, 2, v82
	v_cmp_lt_i32_e32 vcc, v87, v85
	s_mul_i32 s0, s0, 0xc000
	s_add_u32 s10, s19, s0
	s_addc_u32 s11, s20, s1
	s_waitcnt vmcnt(0)
	v_lshlrev_b32_e32 v45, 16, v20
	v_lshlrev_b32_e32 v43, 16, v18
	v_lshlrev_b32_e32 v57, 16, v34
	v_and_b32_e32 v61, 0xffff0000, v34
	v_lshlrev_b32_e32 v56, 16, v94
	v_and_b32_e32 v60, 0xffff0000, v94
	v_lshlrev_b32_e32 v55, 16, v32
	v_and_b32_e32 v59, 0xffff0000, v32
	v_lshlrev_b32_e32 v63, 16, v35
	v_and_b32_e32 v26, 0xffff0000, v78
	v_and_b32_e32 v30, 0xffff0000, v80
	v_lshlrev_b32_e32 v54, 16, v92
	v_and_b32_e32 v58, 0xffff0000, v92
	v_lshlrev_b32_e32 v62, 16, v95
	v_lshlrev_b32_e32 v42, 16, v78
	v_lshlrev_b32_e32 v44, 16, v80
	v_lshlrev_b32_e32 v46, 16, v79
	v_and_b32_e32 v48, 0xffff0000, v79
	v_lshlrev_b32_e32 v50, 16, v81
	v_and_b32_e32 v52, 0xffff0000, v81
	v_pk_mul_f32 v[78:79], v[56:57], v[56:57]
	v_pk_mul_f32 v[80:81], v[60:61], v[60:61]
	v_lshlrev_b32_e32 v65, 16, v33
	v_and_b32_e32 v69, 0xffff0000, v35
	v_lshlrev_b32_e32 v64, 16, v93
	v_and_b32_e32 v66, 0xffff0000, v93
	v_and_b32_e32 v68, 0xffff0000, v95
	v_pk_mul_f32 v[92:93], v[62:63], v[62:63]
	v_pk_fma_f32 v[78:79], v[54:55], v[54:55], v[78:79]
	v_pk_fma_f32 v[80:81], v[58:59], v[58:59], v[80:81]
	v_and_b32_e32 v67, 0xffff0000, v33
	v_pk_mul_f32 v[94:95], v[68:69], v[68:69]
	v_pk_fma_f32 v[92:93], v[64:65], v[64:65], v[92:93]
	v_pk_add_f32 v[78:79], v[78:79], v[80:81]
	v_pk_fma_f32 v[80:81], v[66:67], v[66:67], v[94:95]
	v_pk_add_f32 v[78:79], v[92:93], v[78:79]
	v_and_b32_e32 v31, 0xffff0000, v20
	v_pk_add_f32 v[78:79], v[80:81], v[78:79]
	v_pk_mul_f32 v[80:81], v[44:45], v[44:45]
	v_and_b32_e32 v27, 0xffff0000, v18
	v_pk_fma_f32 v[80:81], v[42:43], v[42:43], v[80:81]
	v_lshlrev_b32_e32 v51, 16, v21
	v_pk_add_f32 v[78:79], v[80:81], v[78:79]
	v_pk_mul_f32 v[80:81], v[30:31], v[30:31]
	v_lshlrev_b32_e32 v47, 16, v19
	v_pk_fma_f32 v[80:81], v[26:27], v[26:27], v[80:81]
	v_and_b32_e32 v49, 0xffff0000, v19
	v_and_b32_e32 v18, 0xffff0000, v4
	v_lshlrev_b32_e32 v19, 16, v4
	v_pk_add_f32 v[78:79], v[80:81], v[78:79]
	v_pk_mul_f32 v[80:81], v[50:51], v[50:51]
	v_and_b32_e32 v70, 0xffff0000, v22
	v_lshlrev_b32_e32 v71, 16, v22
	v_and_b32_e32 v72, 0xffff0000, v24
	v_lshlrev_b32_e32 v73, 16, v24
	v_and_b32_e32 v53, 0xffff0000, v21
	v_and_b32_e32 v20, 0xffff0000, v2
	v_lshlrev_b32_e32 v21, 16, v2
	v_lshlrev_b32_e32 v22, 16, v96
	v_and_b32_e32 v24, 0xffff0000, v96
	v_lshlrev_b32_e32 v28, 16, v97
	v_and_b32_e32 v32, 0xffff0000, v97
	v_pk_mul_f32 v[96:97], v[18:19], v[18:19]
	v_pk_fma_f32 v[80:81], v[46:47], v[46:47], v[80:81]
	v_pk_fma_f32 v[116:117], v[20:21], v[20:21], v[96:97]
	v_pk_add_f32 v[96:97], v[80:81], v[78:79]
	global_load_dwordx4 v[128:131], v1, s[14:15] offset:16
	global_load_dwordx4 v[132:135], v1, s[14:15]
	global_load_dwordx4 v[136:139], v[8:9], off offset:16
	global_load_dwordx4 v[140:143], v[8:9], off
	global_load_dwordx4 v[144:147], v1, s[16:17] offset:16
	global_load_dwordx4 v[148:151], v1, s[16:17]
	global_load_dwordx4 v[152:155], v[8:9], off offset:2048
	global_load_dwordx4 v[156:159], v1, s[14:15] offset:2048
	global_load_dwordx4 v[160:163], v1, s[16:17] offset:2048
	global_load_dwordx4 v[164:167], v[8:9], off offset:2064
	global_load_dwordx4 v[168:171], v1, s[14:15] offset:2064
	global_load_dwordx4 v[172:175], v1, s[16:17] offset:2064
	global_load_dwordx4 v[176:179], v[10:11], off
	global_load_dwordx4 v[180:183], v17, s[14:15]
	global_load_dwordx4 v[184:187], v[10:11], off offset:16
	global_load_dwordx4 v[188:191], v17, s[14:15] offset:16
	global_load_dwordx4 v[192:195], v17, s[16:17]
	global_load_dwordx4 v[196:199], v17, s[16:17] offset:16
	global_load_dwordx4 v[200:203], v[12:13], off
	global_load_dwordx4 v[204:207], v83, s[14:15]
	global_load_dwordx4 v[208:211], v[12:13], off offset:16
	global_load_dwordx4 v[212:215], v83, s[14:15] offset:16
	global_load_dwordx4 v[216:219], v83, s[16:17]
	global_load_dwordx4 v[220:223], v83, s[16:17] offset:16
	v_and_b32_e32 v74, 0xffff0000, v23
	v_lshlrev_b32_e32 v75, 16, v23
	v_and_b32_e32 v76, 0xffff0000, v25
	v_lshlrev_b32_e32 v77, 16, v25
	v_lshlrev_b32_e32 v23, 16, v38
	v_and_b32_e32 v25, 0xffff0000, v38
	v_lshlrev_b32_e32 v35, 16, v40
	v_and_b32_e32 v37, 0xffff0000, v40
	v_lshlrev_b32_e32 v34, 16, v98
	v_and_b32_e32 v36, 0xffff0000, v98
	v_lshlrev_b32_e32 v38, 16, v99
	v_and_b32_e32 v40, 0xffff0000, v99
	v_pk_mul_f32 v[98:99], v[52:53], v[52:53]
	v_lshlrev_b32_e32 v29, 16, v39
	v_pk_fma_f32 v[98:99], v[48:49], v[48:49], v[98:99]
	v_and_b32_e32 v33, 0xffff0000, v39
	v_pk_add_f32 v[96:97], v[98:99], v[96:97]
; __device__ __forceinline__ unsigned pk2(float lo, float hi) { return f2bf(lo) | (f2bf(hi) << 16); }
; template <bool ZP, bool XF32, bool OUT8 = false>
; __device__ __forceinline__ void norm_phase(LAS unsigned char* lds, const void* xin, const float* gain, const float* sh, const float* sc, bf16* hout, const float* wzt, float* zout, int lane, int wave, int vcu, int G) {
;     ...
;                 for (int e = 0; e < 4; ++e) ss[r] += v[r][j][0][e] * v[r][j][0][e] + v[r][j][1][e] * v[r][j][1][e];
; #pragma unroll
;         for (int r = 0; r < 2; ++r) { const int m = m0 + r, b = m >> 11;
;             const float rstd = rsqrtf(wave_sum(ss[r]) * (1.0f / D) + EPS);
; #pragma unroll
;             for (int j = 0; j < 4; ++j) { const int col = 512 * j + 8 * lane;
; #pragma unroll
;                 for (int q = 0; q < 2; ++q) { const f32x4 gg = *(const f32x4*)(gain + col + 4 * q), s1 = *(const f32x4*)(sc + (size_t)b * MODW + col + 4 * q), s0 = *(const f32x4*)(sh + (size_t)b * MODW + col + 4 * q);
;                     v[r][j][q] = (v[r][j][q] * rstd * gg) * (s1 + 1.0f) + s0; }
;                 if constexpr (OUT8) { *(v2u*)((unsigned char*)hout + (size_t)m * D + col) = pack8_fp8(v[r][j][0][0], v[r][j][0][1], v[r][j][0][2], v[r][j][0][3], v[r][j][1][0], v[r][j][1][1], v[r][j][1][2], v[r][j][1][3], FP8_ASCALE); }
;                 else { v4u o; o.x = pk2(v[r][j][0][0], v[r][j][0][1]); o.y = pk2(v[r][j][0][2], v[r][j][0][3]); o.z = pk2(v[r][j][1][0], v[r][j][1][1]); o.w = pk2(v[r][j][1][2], v[r][j][1][3]);
;                     *(v4u*)(hout + (size_t)m * D + col) = o; } }
	v_pk_mul_f32 v[98:99], v[34:35], v[34:35]
	v_lshlrev_b32_e32 v39, 16, v41
	v_pk_fma_f32 v[98:99], v[22:23], v[22:23], v[98:99]
	v_and_b32_e32 v41, 0xffff0000, v41
	v_pk_add_f32 v[96:97], v[98:99], v[96:97]
	v_pk_mul_f32 v[98:99], v[36:37], v[36:37]
	v_pk_mul_f32 v[100:101], v[72:73], v[72:73]
	v_pk_fma_f32 v[98:99], v[24:25], v[24:25], v[98:99]
	v_pk_mul_f32 v[102:103], v[76:77], v[76:77]
	v_pk_add_f32 v[96:97], v[98:99], v[96:97]
	v_pk_mul_f32 v[98:99], v[38:39], v[38:39]
	v_pk_fma_f32 v[112:113], v[70:71], v[70:71], v[100:101]
	v_pk_fma_f32 v[98:99], v[28:29], v[28:29], v[98:99]
	v_pk_fma_f32 v[114:115], v[74:75], v[74:75], v[102:103]
	v_pk_add_f32 v[96:97], v[98:99], v[96:97]
	v_pk_mul_f32 v[98:99], v[40:41], v[40:41]
	v_mov_b32_e32 v120, v117
	v_pk_fma_f32 v[98:99], v[32:33], v[32:33], v[98:99]
	v_mov_b32_e32 v121, v113
	v_pk_add_f32 v[118:119], v[98:99], v[96:97]
	v_and_b32_e32 v4, 0xffff0000, v5
	v_lshlrev_b32_e32 v5, 16, v5
	v_pk_add_f32 v[118:119], v[120:121], v[118:119]
	v_and_b32_e32 v2, 0xffff0000, v3
	v_lshlrev_b32_e32 v3, 16, v3
	v_pk_mul_f32 v[120:121], v[4:5], v[4:5]
	v_mov_b32_e32 v117, v112
	v_pk_fma_f32 v[120:121], v[2:3], v[2:3], v[120:121]
	v_pk_add_f32 v[112:113], v[116:117], v[118:119]
	v_mov_b32_e32 v116, v121
	v_mov_b32_e32 v117, v115
	v_pk_add_f32 v[112:113], v[116:117], v[112:113]
	v_mov_b32_e32 v121, v114
	v_pk_add_f32 v[112:113], v[120:121], v[112:113]
	ds_bpermute_b32 v115, v82, v113
	ds_bpermute_b32 v114, v82, v112
	v_cndmask_b32_e32 v82, v84, v87, vcc
	v_lshlrev_b32_e32 v82, 2, v82
	v_cmp_lt_i32_e32 vcc, v88, v85
	v_mov_b32_e32 v122, v35
	s_waitcnt lgkmcnt(0)
	v_pk_add_f32 v[112:113], v[112:113], v[114:115]
	ds_bpermute_b32 v115, v82, v113
	ds_bpermute_b32 v114, v82, v112
	v_cndmask_b32_e32 v82, v84, v88, vcc
	v_lshlrev_b32_e32 v82, 2, v82
	v_cmp_lt_i32_e32 vcc, v89, v85
	v_mov_b32_e32 v123, v37
	s_waitcnt lgkmcnt(0)
	v_pk_add_f32 v[112:113], v[112:113], v[114:115]
	ds_bpermute_b32 v115, v82, v113
	ds_bpermute_b32 v114, v82, v112
	v_cndmask_b32_e32 v82, v84, v89, vcc
	v_lshlrev_b32_e32 v82, 2, v82
	v_cmp_lt_i32_e32 vcc, v90, v85
	v_mov_b32_e32 v120, v39
	s_waitcnt lgkmcnt(0)
	v_pk_add_f32 v[112:113], v[112:113], v[114:115]
	ds_bpermute_b32 v115, v82, v113
	ds_bpermute_b32 v114, v82, v112
	v_cndmask_b32_e32 v82, v84, v90, vcc
	v_lshlrev_b32_e32 v82, 2, v82
	v_cmp_lt_i32_e32 vcc, v91, v85
	s_waitcnt vmcnt(0)
	v_mov_b64_e32 v[92:93], v[128:129]
	v_mov_b64_e32 v[94:95], v[130:131]
	v_mov_b64_e32 v[78:79], v[132:133]
	v_mov_b64_e32 v[80:81], v[134:135]
	v_mov_b64_e32 v[96:97], v[136:137]
	v_mov_b64_e32 v[98:99], v[138:139]
	v_mov_b64_e32 v[100:101], v[140:141]
	v_mov_b64_e32 v[102:103], v[142:143]
	v_mov_b64_e32 v[104:105], v[144:145]
	v_mov_b64_e32 v[106:107], v[146:147]
	v_mov_b64_e32 v[108:109], v[148:149]
	v_mov_b64_e32 v[110:111], v[150:151]
	global_load_dwordx4 v[248:251], v[244:245], off offset:1024
	global_load_dwordx4 v[248:251], v[244:245], off offset:3072
	global_load_dwordx4 v[248:251], v[244:245], off
	global_load_dwordx4 v[248:251], v[244:245], off offset:2048
	global_load_dwordx4 v[248:251], v[246:247], off offset:1024
	global_load_dwordx4 v[248:251], v[246:247], off
	global_load_dwordx4 v[248:251], v[246:247], off offset:3072
	global_load_dwordx4 v[248:251], v[246:247], off offset:2048
	v_pk_add_f32 v[94:95], v[94:95], 1.0 op_sel_hi:[1,0]
	s_waitcnt lgkmcnt(0)
	v_pk_add_f32 v[112:113], v[112:113], v[114:115]
	ds_bpermute_b32 v115, v82, v113
	ds_bpermute_b32 v114, v82, v112
	v_cndmask_b32_e32 v82, v84, v91, vcc
	v_lshlrev_b32_e32 v82, 2, v82
	v_pk_add_f32 v[118:119], v[78:79], 1.0 op_sel_hi:[1,0]
	v_pk_add_f32 v[116:117], v[80:81], 1.0 op_sel_hi:[1,0]
	s_waitcnt lgkmcnt(0)
	v_pk_add_f32 v[112:113], v[112:113], v[114:115]
	ds_bpermute_b32 v115, v82, v113
	ds_bpermute_b32 v114, v82, v112
	v_pk_add_f32 v[92:93], v[92:93], 1.0 op_sel_hi:[1,0]
	v_mov_b32_e32 v121, v41
	v_pk_mov_b32 v[74:75], v[74:75], v[74:75] op_sel:[1,0]
	v_pk_mov_b32 v[76:77], v[76:77], v[76:77] op_sel:[1,0]
	s_waitcnt lgkmcnt(0)
	v_pk_add_f32 v[78:79], v[112:113], v[114:115]
	v_mov_b32_e32 v114, v55
	v_pk_fma_f32 v[78:79], v[78:79], s[6:7], v[16:17] op_sel_hi:[1,0,0]
	v_mov_b32_e32 v115, v59
	v_mul_f32_e32 v80, 0x4b800000, v79
	v_cmp_gt_f32_e32 vcc, s26, v79
	v_mov_b32_e32 v112, v65
	v_mov_b32_e32 v113, v67
	v_cndmask_b32_e32 v79, v79, v80, vcc
	v_rsq_f32_e32 v79, v79
	v_lshl_add_u64 v[80:81], v[14:15], 0, s[12:13]
	s_add_u32 s12, s7, s0
	s_addc_u32 s13, s18, s1
	v_mul_f32_e32 v82, 0x45800000, v79
	v_cndmask_b32_e32 v82, v79, v82, vcc
	v_pk_mul_f32 v[114:115], v[82:83], v[114:115] op_sel_hi:[0,1]
	v_pk_mul_f32 v[112:113], v[82:83], v[112:113] op_sel_hi:[0,1]
	v_pk_mul_f32 v[122:123], v[82:83], v[122:123] op_sel_hi:[0,1]
	v_pk_mul_f32 v[120:121], v[82:83], v[120:121] op_sel_hi:[0,1]
	v_pk_mul_f32 v[76:77], v[82:83], v[76:77] op_sel_hi:[0,1]
	v_cmp_gt_f32_e32 vcc, s26, v78
	v_mov_b32_e32 v65, v66
	v_pk_mul_f32 v[100:101], v[100:101], v[114:115]
	v_pk_mul_f32 v[102:103], v[102:103], v[112:113]
	v_pk_fma_f32 v[100:101], v[118:119], v[100:101], v[108:109]
	v_pk_fma_f32 v[102:103], v[116:117], v[102:103], v[110:111]
	v_mov_b32_e32 v108, v63
	v_mov_b32_e32 v109, v69
	v_mov_b32_e32 v110, v57
	v_mov_b32_e32 v111, v61
	v_bfe_u32 v55, v100, 16, 1
	v_pk_mul_f32 v[108:109], v[82:83], v[108:109] op_sel_hi:[0,1]
	v_pk_mul_f32 v[110:111], v[82:83], v[110:111] op_sel_hi:[0,1]
	v_add3_u32 v55, v100, v55, s27
	v_bfe_u32 v57, v101, 16, 1
	v_pk_mul_f32 v[96:97], v[96:97], v[110:111]
	v_pk_mul_f32 v[98:99], v[98:99], v[108:109]
	v_lshrrev_b32_e32 v55, 16, v55
	v_add3_u32 v57, v101, v57, s27
	v_pk_fma_f32 v[98:99], v[94:95], v[98:99], v[106:107]
; __device__ __forceinline__ unsigned pk2(float lo, float hi) { return f2bf(lo) | (f2bf(hi) << 16); }
; template <bool ZP, bool XF32, bool OUT8 = false>
; __device__ __forceinline__ void norm_phase(LAS unsigned char* lds, const void* xin, const float* gain, const float* sh, const float* sc, bf16* hout, const float* wzt, float* zout, int lane, int wave, int vcu, int G) {
;     ...
;         for (int r = 0; r < 2; ++r) { const int m = m0 + r, b = m >> 11;
;             const float rstd = rsqrtf(wave_sum(ss[r]) * (1.0f / D) + EPS);
; #pragma unroll
;             for (int j = 0; j < 4; ++j) { const int col = 512 * j + 8 * lane;
; #pragma unroll
;                 for (int q = 0; q < 2; ++q) { const f32x4 gg = *(const f32x4*)(gain + col + 4 * q), s1 = *(const f32x4*)(sc + (size_t)b * MODW + col + 4 * q), s0 = *(const f32x4*)(sh + (size_t)b * MODW + col + 4 * q);
;                     v[r][j][q] = (v[r][j][q] * rstd * gg) * (s1 + 1.0f) + s0; }
;                 if constexpr (OUT8) { *(v2u*)((unsigned char*)hout + (size_t)m * D + col) = pack8_fp8(v[r][j][0][0], v[r][j][0][1], v[r][j][0][2], v[r][j][0][3], v[r][j][1][0], v[r][j][1][1], v[r][j][1][2], v[r][j][1][3], FP8_ASCALE); }
;                 else { v4u o; o.x = pk2(v[r][j][0][0], v[r][j][0][1]); o.y = pk2(v[r][j][0][2], v[r][j][0][3]); o.z = pk2(v[r][j][1][0], v[r][j][1][1]); o.w = pk2(v[r][j][1][2], v[r][j][1][3]);
;                     *(v4u*)(hout + (size_t)m * D + col) = o; } }
	v_pk_fma_f32 v[94:95], v[92:93], v[96:97], v[104:105]
	v_and_or_b32 v92, v57, s25, v55
	v_bfe_u32 v55, v102, 16, 1
	v_add3_u32 v55, v102, v55, s27
	v_bfe_u32 v57, v103, 16, 1
	v_lshrrev_b32_e32 v55, 16, v55
	v_add3_u32 v57, v103, v57, s27
	v_and_or_b32 v93, v57, s25, v55
	v_bfe_u32 v55, v94, 16, 1
	v_add3_u32 v55, v94, v55, s27
	v_bfe_u32 v57, v95, 16, 1
	v_lshrrev_b32_e32 v55, 16, v55
	v_add3_u32 v57, v95, v57, s27
	v_and_or_b32 v94, v57, s25, v55
	v_bfe_u32 v55, v98, 16, 1
	v_add3_u32 v55, v98, v55, s27
	v_bfe_u32 v57, v99, 16, 1
	v_lshrrev_b32_e32 v55, 16, v55
	v_add3_u32 v57, v99, v57, s27
	v_and_or_b32 v95, v57, s25, v55
	global_store_dwordx4 v[80:81], v[92:95], off
	s_nop 1
	v_mov_b64_e32 v[92:93], v[152:153]
	v_mov_b64_e32 v[94:95], v[154:155]
	s_nop 0
	s_nop 1
	v_mov_b64_e32 v[96:97], v[156:157]
	v_mov_b64_e32 v[98:99], v[158:159]
	v_mov_b64_e32 v[100:101], v[160:161]
	v_mov_b64_e32 v[102:103], v[162:163]
	v_mov_b64_e32 v[104:105], v[164:165]
	v_mov_b64_e32 v[106:107], v[166:167]
	v_mov_b64_e32 v[108:109], v[168:169]
	v_mov_b64_e32 v[110:111], v[170:171]
	v_mov_b64_e32 v[112:113], v[172:173]
	v_mov_b64_e32 v[114:115], v[174:175]
	v_mov_b32_e32 v118, v43
	v_mov_b32_e32 v119, v27
	v_pk_mul_f32 v[118:119], v[82:83], v[118:119] op_sel_hi:[0,1]
	v_mov_b32_e32 v116, v47
	v_mov_b32_e32 v117, v49
	v_pk_mul_f32 v[116:117], v[82:83], v[116:117] op_sel_hi:[0,1]
	v_mov_b32_e32 v63, v68
	v_mov_b32_e32 v57, v60
	v_mov_b32_e32 v55, v58
	v_mov_b32_e32 v47, v48
	v_mov_b32_e32 v43, v26
	v_pk_mov_b32 v[2:3], v[2:3], v[2:3] op_sel:[1,0]
	v_pk_mov_b32 v[4:5], v[4:5], v[4:5] op_sel:[1,0]
	s_add_i32 s24, s24, 1
	s_addk_i32 s23, 0x200
	s_add_i32 s3, s3, -1
	s_cmp_eq_u32 s3, 0
	v_pk_mul_f32 v[92:93], v[92:93], v[118:119]
	v_pk_add_f32 v[96:97], v[96:97], 1.0 op_sel_hi:[1,0]
	v_pk_mul_f32 v[94:95], v[94:95], v[116:117]
	v_pk_fma_f32 v[92:93], v[96:97], v[92:93], v[100:101]
	v_pk_add_f32 v[98:99], v[98:99], 1.0 op_sel_hi:[1,0]
	v_bfe_u32 v27, v92, 16, 1
	v_pk_fma_f32 v[94:95], v[98:99], v[94:95], v[102:103]
	v_mov_b32_e32 v99, v31
	v_add3_u32 v27, v92, v27, s27
	v_bfe_u32 v31, v93, 16, 1
	v_mov_b32_e32 v98, v45
	v_lshrrev_b32_e32 v27, 16, v27
	v_add3_u32 v31, v93, v31, s27
	v_pk_mul_f32 v[98:99], v[82:83], v[98:99] op_sel_hi:[0,1]
	v_and_or_b32 v92, v31, s25, v27
	v_bfe_u32 v27, v94, 16, 1
	v_pk_mul_f32 v[98:99], v[104:105], v[98:99]
	v_pk_add_f32 v[102:103], v[108:109], 1.0 op_sel_hi:[1,0]
	v_add3_u32 v27, v94, v27, s27
	v_bfe_u32 v31, v95, 16, 1
	v_mov_b32_e32 v96, v51
	v_mov_b32_e32 v97, v53
	v_pk_fma_f32 v[98:99], v[102:103], v[98:99], v[112:113]
	v_lshrrev_b32_e32 v27, 16, v27
	v_add3_u32 v31, v95, v31, s27
	v_pk_mul_f32 v[96:97], v[82:83], v[96:97] op_sel_hi:[0,1]
	v_and_or_b32 v93, v31, s25, v27
	v_bfe_u32 v27, v98, 16, 1
	v_pk_mul_f32 v[96:97], v[106:107], v[96:97]
	v_pk_add_f32 v[100:101], v[110:111], 1.0 op_sel_hi:[1,0]
	v_add3_u32 v27, v98, v27, s27
	v_bfe_u32 v31, v99, 16, 1
	v_pk_fma_f32 v[96:97], v[100:101], v[96:97], v[114:115]
	v_lshrrev_b32_e32 v27, 16, v27
	v_add3_u32 v31, v99, v31, s27
	v_and_or_b32 v94, v31, s25, v27
	v_bfe_u32 v27, v96, 16, 1
	v_add3_u32 v27, v96, v27, s27
	v_bfe_u32 v31, v97, 16, 1
	v_lshrrev_b32_e32 v27, 16, v27
	v_add3_u32 v31, v97, v31, s27
	v_and_or_b32 v95, v31, s25, v27
	global_store_dwordx4 v[80:81], v[92:95], off offset:1024
	s_nop 1
	v_mov_b64_e32 v[92:93], v[176:177]
	v_mov_b64_e32 v[94:95], v[178:179]
	s_nop 0
	s_nop 1
	v_mov_b64_e32 v[96:97], v[180:181]
	v_mov_b64_e32 v[98:99], v[182:183]
	v_mov_b64_e32 v[100:101], v[184:185]
	v_mov_b64_e32 v[102:103], v[186:187]
	v_mov_b64_e32 v[104:105], v[188:189]
	v_mov_b64_e32 v[106:107], v[190:191]
	v_mov_b64_e32 v[108:109], v[192:193]
	v_mov_b64_e32 v[110:111], v[194:195]
	v_mov_b64_e32 v[112:113], v[196:197]
	v_mov_b64_e32 v[114:115], v[198:199]
	v_mov_b32_e32 v118, v23
	v_mov_b32_e32 v119, v25
	v_pk_mul_f32 v[118:119], v[82:83], v[118:119] op_sel_hi:[0,1]
	v_mov_b32_e32 v116, v29
	v_mov_b32_e32 v117, v33
	v_pk_mul_f32 v[116:117], v[82:83], v[116:117] op_sel_hi:[0,1]
	v_mov_b32_e32 v51, v52
	v_mov_b32_e32 v45, v30
	v_pk_mul_f32 v[92:93], v[92:93], v[118:119]
	v_pk_add_f32 v[96:97], v[96:97], 1.0 op_sel_hi:[1,0]
	v_pk_mul_f32 v[94:95], v[94:95], v[116:117]
	v_pk_add_f32 v[98:99], v[98:99], 1.0 op_sel_hi:[1,0]
	v_pk_fma_f32 v[92:93], v[96:97], v[92:93], v[108:109]
	v_pk_fma_f32 v[94:95], v[98:99], v[94:95], v[110:111]
	v_bfe_u32 v23, v92, 16, 1
	v_bfe_u32 v25, v93, 16, 1
	v_add3_u32 v23, v92, v23, s27
	v_lshrrev_b32_e32 v23, 16, v23
	v_add3_u32 v25, v93, v25, s27
	v_and_or_b32 v92, v25, s25, v23
	v_bfe_u32 v23, v94, 16, 1
	v_pk_mul_f32 v[100:101], v[100:101], v[122:123]
	v_pk_add_f32 v[104:105], v[104:105], 1.0 op_sel_hi:[1,0]
	v_add3_u32 v23, v94, v23, s27
	v_bfe_u32 v25, v95, 16, 1
	v_pk_fma_f32 v[98:99], v[104:105], v[100:101], v[112:113]
	v_lshrrev_b32_e32 v23, 16, v23
	v_add3_u32 v25, v95, v25, s27
	v_and_or_b32 v93, v25, s25, v23
	v_bfe_u32 v23, v98, 16, 1
	v_pk_mul_f32 v[102:103], v[102:103], v[120:121]
	v_pk_add_f32 v[106:107], v[106:107], 1.0 op_sel_hi:[1,0]
	v_add3_u32 v23, v98, v23, s27
	v_bfe_u32 v25, v99, 16, 1
	v_pk_fma_f32 v[96:97], v[106:107], v[102:103], v[114:115]
	v_lshrrev_b32_e32 v23, 16, v23
	v_add3_u32 v25, v99, v25, s27
	v_and_or_b32 v94, v25, s25, v23
	v_bfe_u32 v23, v96, 16, 1
	v_add3_u32 v23, v96, v23, s27
	v_bfe_u32 v25, v97, 16, 1
	v_lshrrev_b32_e32 v23, 16, v23
	v_add3_u32 v25, v97, v25, s27
	v_and_or_b32 v95, v25, s25, v23
	global_store_dwordx4 v[80:81], v[92:95], off offset:2048
	s_nop 1
	v_mov_b64_e32 v[92:93], v[200:201]
	v_mov_b64_e32 v[94:95], v[202:203]
	s_nop 0
	s_nop 1
	v_mov_b64_e32 v[96:97], v[204:205]
	v_mov_b64_e32 v[98:99], v[206:207]
; __device__ __forceinline__ unsigned pk2(float lo, float hi) { return f2bf(lo) | (f2bf(hi) << 16); }
; template <bool ZP, bool XF32, bool OUT8 = false>
; __device__ __forceinline__ void norm_phase(LAS unsigned char* lds, const void* xin, const float* gain, const float* sh, const float* sc, bf16* hout, const float* wzt, float* zout, int lane, int wave, int vcu, int G) {
;     ...
;         for (int r = 0; r < 2; ++r) { const int m = m0 + r, b = m >> 11;
;             const float rstd = rsqrtf(wave_sum(ss[r]) * (1.0f / D) + EPS);
; #pragma unroll
;             for (int j = 0; j < 4; ++j) { const int col = 512 * j + 8 * lane;
; #pragma unroll
;                 for (int q = 0; q < 2; ++q) { const f32x4 gg = *(const f32x4*)(gain + col + 4 * q), s1 = *(const f32x4*)(sc + (size_t)b * MODW + col + 4 * q), s0 = *(const f32x4*)(sh + (size_t)b * MODW + col + 4 * q);
;                     v[r][j][q] = (v[r][j][q] * rstd * gg) * (s1 + 1.0f) + s0; }
;                 if constexpr (OUT8) { *(v2u*)((unsigned char*)hout + (size_t)m * D + col) = pack8_fp8(v[r][j][0][0], v[r][j][0][1], v[r][j][0][2], v[r][j][0][3], v[r][j][1][0], v[r][j][1][1], v[r][j][1][2], v[r][j][1][3], FP8_ASCALE); }
;                 else { v4u o; o.x = pk2(v[r][j][0][0], v[r][j][0][1]); o.y = pk2(v[r][j][0][2], v[r][j][0][3]); o.z = pk2(v[r][j][1][0], v[r][j][1][1]); o.w = pk2(v[r][j][1][2], v[r][j][1][3]);
;                     *(v4u*)(hout + (size_t)m * D + col) = o; } }
	v_mov_b64_e32 v[100:101], v[208:209]
	v_mov_b64_e32 v[102:103], v[210:211]
	v_mov_b64_e32 v[104:105], v[212:213]
	v_mov_b64_e32 v[106:107], v[214:215]
	v_mov_b64_e32 v[108:109], v[216:217]
	v_mov_b64_e32 v[110:111], v[218:219]
	v_mov_b64_e32 v[112:113], v[220:221]
	v_mov_b64_e32 v[114:115], v[222:223]
	v_mov_b32_e32 v116, v71
	v_mov_b32_e32 v117, v70
	v_mov_b32_e32 v70, v73
	v_mov_b32_e32 v71, v72
	v_pk_mul_f32 v[72:73], v[82:83], v[74:75] op_sel_hi:[0,1]
	v_pk_mul_f32 v[74:75], v[82:83], v[116:117] op_sel_hi:[0,1]
	v_pk_mul_f32 v[70:71], v[82:83], v[70:71] op_sel_hi:[0,1]
	v_pk_mul_f32 v[74:75], v[74:75], v[92:93]
	v_pk_mul_f32 v[72:73], v[72:73], v[94:95]
	v_pk_add_f32 v[92:93], v[98:99], 1.0 op_sel_hi:[1,0]
	v_pk_add_f32 v[94:95], v[96:97], 1.0 op_sel_hi:[1,0]
	v_pk_mul_f32 v[70:71], v[70:71], v[100:101]
	v_pk_mul_f32 v[76:77], v[76:77], v[102:103]
	v_pk_add_f32 v[96:97], v[106:107], 1.0 op_sel_hi:[1,0]
	v_pk_add_f32 v[98:99], v[104:105], 1.0 op_sel_hi:[1,0]
	v_pk_fma_f32 v[72:73], v[72:73], v[92:93], v[110:111]
	v_pk_fma_f32 v[74:75], v[74:75], v[94:95], v[108:109]
	v_pk_fma_f32 v[76:77], v[76:77], v[96:97], v[114:115]
	v_pk_fma_f32 v[70:71], v[70:71], v[98:99], v[112:113]
	v_bfe_u32 v23, v74, 16, 1
	v_bfe_u32 v27, v72, 16, 1
	v_bfe_u32 v31, v70, 16, 1
	v_bfe_u32 v35, v76, 16, 1
	v_bfe_u32 v25, v75, 16, 1
	v_bfe_u32 v29, v73, 16, 1
	v_bfe_u32 v33, v71, 16, 1
	v_bfe_u32 v37, v77, 16, 1
	v_add3_u32 v23, v74, v23, s27
	v_add3_u32 v27, v72, v27, s27
	v_add3_u32 v31, v70, v31, s27
	v_add3_u32 v35, v76, v35, s27
	v_add3_u32 v25, v75, v25, s27
	v_add3_u32 v29, v73, v29, s27
	v_add3_u32 v33, v71, v33, s27
	v_add3_u32 v37, v77, v37, s27
	v_lshrrev_b32_e32 v23, 16, v23
	v_lshrrev_b32_e32 v27, 16, v27
	v_lshrrev_b32_e32 v31, 16, v31
	v_lshrrev_b32_e32 v35, 16, v35
	v_and_or_b32 v70, v25, s25, v23
	v_and_or_b32 v71, v29, s25, v27
	v_and_or_b32 v72, v33, s25, v31
	v_and_or_b32 v73, v37, s25, v35
	global_store_dwordx4 v[80:81], v[70:73], off offset:3072
	s_nop 1
	v_mov_b64_e32 v[72:73], v[140:141]
	v_mov_b64_e32 v[74:75], v[142:143]
	s_nop 0
	s_nop 1
	v_mov_b64_e32 v[92:93], v[132:133]
	v_mov_b64_e32 v[94:95], v[134:135]
	v_mov_b64_e32 v[96:97], v[136:137]
	v_mov_b64_e32 v[98:99], v[138:139]
	v_mov_b64_e32 v[100:101], v[128:129]
	v_mov_b64_e32 v[102:103], v[130:131]
	v_mov_b64_e32 v[104:105], v[148:149]
	v_mov_b64_e32 v[106:107], v[150:151]
	v_mov_b64_e32 v[108:109], v[144:145]
	v_mov_b64_e32 v[110:111], v[146:147]
	v_mul_f32_e32 v23, 0x4b800000, v78
	v_cndmask_b32_e32 v23, v78, v23, vcc
	v_rsq_f32_e32 v23, v23
	v_lshl_add_u64 v[70:71], v[14:15], 0, s[8:9]
	s_cselect_b64 s[8:9], -1, 0
	v_mul_f32_e32 v25, 0x45800000, v23
	v_cndmask_b32_e32 v58, v23, v25, vcc
	v_pk_mul_f32 v[60:61], v[58:59], v[64:65] op_sel_hi:[0,1]
	v_pk_mul_f32 v[54:55], v[58:59], v[54:55] op_sel_hi:[0,1]
	v_pk_mul_f32 v[62:63], v[58:59], v[62:63] op_sel_hi:[0,1]
	v_pk_mul_f32 v[56:57], v[58:59], v[56:57] op_sel_hi:[0,1]
	v_pk_mul_f32 v[44:45], v[58:59], v[44:45] op_sel_hi:[0,1]
	v_pk_mul_f32 v[2:3], v[58:59], v[2:3] op_sel_hi:[0,1]
	v_pk_mul_f32 v[4:5], v[58:59], v[4:5] op_sel_hi:[0,1]
	v_pk_add_f32 v[64:65], v[94:95], 1.0 op_sel_hi:[1,0]
	v_pk_mul_f32 v[54:55], v[72:73], v[54:55]
	v_pk_mul_f32 v[60:61], v[74:75], v[60:61]
	v_pk_add_f32 v[66:67], v[92:93], 1.0 op_sel_hi:[1,0]
	v_pk_mul_f32 v[56:57], v[96:97], v[56:57]
	v_pk_mul_f32 v[62:63], v[98:99], v[62:63]
	v_pk_add_f32 v[68:69], v[102:103], 1.0 op_sel_hi:[1,0]
	v_pk_add_f32 v[72:73], v[100:101], 1.0 op_sel_hi:[1,0]
	v_pk_fma_f32 v[60:61], v[64:65], v[60:61], v[106:107]
	v_pk_fma_f32 v[54:55], v[66:67], v[54:55], v[104:105]
	v_pk_fma_f32 v[62:63], v[68:69], v[62:63], v[110:111]
	v_pk_fma_f32 v[56:57], v[72:73], v[56:57], v[108:109]
	v_bfe_u32 v23, v54, 16, 1
	v_bfe_u32 v27, v60, 16, 1
	v_bfe_u32 v31, v56, 16, 1
	v_bfe_u32 v35, v62, 16, 1
	v_bfe_u32 v25, v55, 16, 1
	v_bfe_u32 v29, v61, 16, 1
	v_bfe_u32 v33, v57, 16, 1
	v_bfe_u32 v37, v63, 16, 1
	v_add3_u32 v23, v54, v23, s27
	v_add3_u32 v27, v60, v27, s27
	v_add3_u32 v31, v56, v31, s27
	v_add3_u32 v35, v62, v35, s27
	v_add3_u32 v25, v55, v25, s27
	v_add3_u32 v29, v61, v29, s27
	v_add3_u32 v33, v57, v33, s27
	v_add3_u32 v37, v63, v37, s27
	v_lshrrev_b32_e32 v23, 16, v23
	v_lshrrev_b32_e32 v27, 16, v27
	v_lshrrev_b32_e32 v31, 16, v31
	v_lshrrev_b32_e32 v35, 16, v35
	v_and_or_b32 v54, v25, s25, v23
	v_and_or_b32 v55, v29, s25, v27
	v_and_or_b32 v56, v33, s25, v31
	v_and_or_b32 v57, v37, s25, v35
	global_store_dwordx4 v[70:71], v[54:57], off
	s_nop 1
	v_mov_b64_e32 v[54:55], v[152:153]
	v_mov_b64_e32 v[56:57], v[154:155]
	s_nop 0
	s_nop 1
	v_mov_b64_e32 v[60:61], v[156:157]
	v_mov_b64_e32 v[62:63], v[158:159]
	v_mov_b64_e32 v[64:65], v[164:165]
	v_mov_b64_e32 v[66:67], v[166:167]
	v_mov_b64_e32 v[72:73], v[168:169]
	v_mov_b64_e32 v[74:75], v[170:171]
	v_mov_b64_e32 v[76:77], v[160:161]
	v_mov_b64_e32 v[78:79], v[162:163]
	v_mov_b64_e32 v[92:93], v[172:173]
	v_mov_b64_e32 v[94:95], v[174:175]
	v_pk_mul_f32 v[26:27], v[58:59], v[46:47] op_sel_hi:[0,1]
	v_pk_mul_f32 v[30:31], v[58:59], v[42:43] op_sel_hi:[0,1]
	v_pk_mul_f32 v[42:43], v[58:59], v[50:51] op_sel_hi:[0,1]
	v_pk_mul_f32 v[30:31], v[54:55], v[30:31]
	v_pk_mul_f32 v[26:27], v[56:57], v[26:27]
	v_pk_add_f32 v[46:47], v[62:63], 1.0 op_sel_hi:[1,0]
	v_pk_add_f32 v[48:49], v[60:61], 1.0 op_sel_hi:[1,0]
	v_pk_mul_f32 v[44:45], v[64:65], v[44:45]
; __device__ __forceinline__ unsigned pk2(float lo, float hi) { return f2bf(lo) | (f2bf(hi) << 16); }
; template <bool ZP, bool XF32, bool OUT8 = false>
; __device__ __forceinline__ void norm_phase(LAS unsigned char* lds, const void* xin, const float* gain, const float* sh, const float* sc, bf16* hout, const float* wzt, float* zout, int lane, int wave, int vcu, int G) {
;     ...
;         for (int r = 0; r < 2; ++r) { const int m = m0 + r, b = m >> 11;
;             const float rstd = rsqrtf(wave_sum(ss[r]) * (1.0f / D) + EPS);
; #pragma unroll
;             for (int j = 0; j < 4; ++j) { const int col = 512 * j + 8 * lane;
; #pragma unroll
;                 for (int q = 0; q < 2; ++q) { const f32x4 gg = *(const f32x4*)(gain + col + 4 * q), s1 = *(const f32x4*)(sc + (size_t)b * MODW + col + 4 * q), s0 = *(const f32x4*)(sh + (size_t)b * MODW + col + 4 * q);
;                     v[r][j][q] = (v[r][j][q] * rstd * gg) * (s1 + 1.0f) + s0; }
;                 if constexpr (OUT8) { *(v2u*)((unsigned char*)hout + (size_t)m * D + col) = pack8_fp8(v[r][j][0][0], v[r][j][0][1], v[r][j][0][2], v[r][j][0][3], v[r][j][1][0], v[r][j][1][1], v[r][j][1][2], v[r][j][1][3], FP8_ASCALE); }
;                 else { v4u o; o.x = pk2(v[r][j][0][0], v[r][j][0][1]); o.y = pk2(v[r][j][0][2], v[r][j][0][3]); o.z = pk2(v[r][j][1][0], v[r][j][1][1]); o.w = pk2(v[r][j][1][2], v[r][j][1][3]);
;                     *(v4u*)(hout + (size_t)m * D + col) = o; } }
	v_pk_mul_f32 v[42:43], v[66:67], v[42:43]
	v_pk_add_f32 v[50:51], v[74:75], 1.0 op_sel_hi:[1,0]
	v_pk_add_f32 v[52:53], v[72:73], 1.0 op_sel_hi:[1,0]
	v_pk_fma_f32 v[26:27], v[46:47], v[26:27], v[78:79]
	v_pk_fma_f32 v[30:31], v[48:49], v[30:31], v[76:77]
	v_pk_fma_f32 v[42:43], v[50:51], v[42:43], v[94:95]
	v_pk_fma_f32 v[44:45], v[52:53], v[44:45], v[92:93]
	v_bfe_u32 v23, v30, 16, 1
	v_bfe_u32 v25, v31, 16, 1
	v_bfe_u32 v29, v26, 16, 1
	v_bfe_u32 v35, v44, 16, 1
	v_bfe_u32 v39, v42, 16, 1
	v_bfe_u32 v33, v27, 16, 1
	v_bfe_u32 v37, v45, 16, 1
	v_bfe_u32 v41, v43, 16, 1
	v_add3_u32 v23, v30, v23, s27
	v_add3_u32 v25, v31, v25, s27
	v_add3_u32 v26, v26, v29, s27
	v_add3_u32 v29, v44, v35, s27
	v_add3_u32 v31, v42, v39, s27
	v_add3_u32 v27, v27, v33, s27
	v_add3_u32 v30, v45, v37, s27
	v_add3_u32 v33, v43, v41, s27
	v_lshrrev_b32_e32 v23, 16, v23
	v_lshrrev_b32_e32 v26, 16, v26
	v_lshrrev_b32_e32 v29, 16, v29
	v_lshrrev_b32_e32 v31, 16, v31
	v_and_or_b32 v42, v25, s25, v23
	v_and_or_b32 v43, v27, s25, v26
	v_and_or_b32 v44, v30, s25, v29
	v_and_or_b32 v45, v33, s25, v31
	global_store_dwordx4 v[70:71], v[42:45], off offset:1024
	s_nop 1
	v_mov_b64_e32 v[42:43], v[176:177]
	v_mov_b64_e32 v[44:45], v[178:179]
	s_nop 0
	s_nop 1
	v_mov_b64_e32 v[46:47], v[180:181]
	v_mov_b64_e32 v[48:49], v[182:183]
	v_mov_b64_e32 v[50:51], v[184:185]
	v_mov_b64_e32 v[52:53], v[186:187]
	v_mov_b64_e32 v[54:55], v[188:189]
	v_mov_b64_e32 v[56:57], v[190:191]
	v_mov_b64_e32 v[60:61], v[192:193]
	v_mov_b64_e32 v[62:63], v[194:195]
	v_mov_b64_e32 v[64:65], v[196:197]
	v_mov_b64_e32 v[66:67], v[198:199]
	v_mov_b32_e32 v39, v40
	v_mov_b32_e32 v35, v36
	v_mov_b32_e32 v29, v32
	v_mov_b32_e32 v23, v24
	v_pk_mul_f32 v[24:25], v[58:59], v[28:29] op_sel_hi:[0,1]
	v_pk_mul_f32 v[22:23], v[58:59], v[22:23] op_sel_hi:[0,1]
	v_pk_mul_f32 v[26:27], v[58:59], v[38:39] op_sel_hi:[0,1]
	v_pk_mul_f32 v[28:29], v[58:59], v[34:35] op_sel_hi:[0,1]
	v_pk_mul_f32 v[22:23], v[22:23], v[42:43]
	v_pk_mul_f32 v[24:25], v[24:25], v[44:45]
	v_pk_add_f32 v[30:31], v[48:49], 1.0 op_sel_hi:[1,0]
	v_pk_add_f32 v[32:33], v[46:47], 1.0 op_sel_hi:[1,0]
	v_pk_mul_f32 v[28:29], v[28:29], v[50:51]
	v_pk_mul_f32 v[26:27], v[26:27], v[52:53]
	v_pk_add_f32 v[34:35], v[56:57], 1.0 op_sel_hi:[1,0]
	v_pk_add_f32 v[36:37], v[54:55], 1.0 op_sel_hi:[1,0]
	v_pk_fma_f32 v[24:25], v[24:25], v[30:31], v[62:63]
	v_pk_fma_f32 v[22:23], v[22:23], v[32:33], v[60:61]
	v_pk_fma_f32 v[26:27], v[26:27], v[34:35], v[66:67]
	v_pk_fma_f32 v[28:29], v[28:29], v[36:37], v[64:65]
	v_bfe_u32 v30, v22, 16, 1
	v_bfe_u32 v32, v24, 16, 1
	v_bfe_u32 v34, v28, 16, 1
	v_bfe_u32 v36, v26, 16, 1
	v_bfe_u32 v31, v23, 16, 1
	v_bfe_u32 v33, v25, 16, 1
	v_bfe_u32 v35, v29, 16, 1
	v_bfe_u32 v37, v27, 16, 1
	v_add3_u32 v22, v22, v30, s27
	v_add3_u32 v24, v24, v32, s27
	v_add3_u32 v28, v28, v34, s27
	v_add3_u32 v26, v26, v36, s27
	v_add3_u32 v23, v23, v31, s27
	v_add3_u32 v25, v25, v33, s27
	v_add3_u32 v29, v29, v35, s27
	v_add3_u32 v27, v27, v37, s27
	v_lshrrev_b32_e32 v22, 16, v22
	v_lshrrev_b32_e32 v24, 16, v24
	v_lshrrev_b32_e32 v28, 16, v28
	v_lshrrev_b32_e32 v26, 16, v26
	v_and_or_b32 v22, v23, s25, v22
	v_and_or_b32 v23, v25, s25, v24
	v_and_or_b32 v24, v29, s25, v28
	v_and_or_b32 v25, v27, s25, v26
	global_store_dwordx4 v[70:71], v[22:25], off offset:2048
	s_nop 1
	v_mov_b64_e32 v[22:23], v[200:201]
	v_mov_b64_e32 v[24:25], v[202:203]
	s_nop 0
	s_nop 1
	v_mov_b64_e32 v[26:27], v[204:205]
	v_mov_b64_e32 v[28:29], v[206:207]
	v_mov_b64_e32 v[30:31], v[208:209]
	v_mov_b64_e32 v[32:33], v[210:211]
	v_mov_b64_e32 v[34:35], v[212:213]
	v_mov_b64_e32 v[36:37], v[214:215]
	v_mov_b64_e32 v[38:39], v[216:217]
	v_mov_b64_e32 v[40:41], v[218:219]
	v_mov_b64_e32 v[42:43], v[220:221]
	v_mov_b64_e32 v[44:45], v[222:223]
	v_mov_b32_e32 v46, v21
	v_mov_b32_e32 v47, v20
	v_mov_b32_e32 v20, v19
	v_mov_b32_e32 v21, v18
	v_pk_mul_f32 v[18:19], v[58:59], v[46:47] op_sel_hi:[0,1]
	v_pk_mul_f32 v[20:21], v[58:59], v[20:21] op_sel_hi:[0,1]
	v_pk_mul_f32 v[18:19], v[18:19], v[22:23]
	v_pk_mul_f32 v[2:3], v[2:3], v[24:25]
	v_pk_add_f32 v[22:23], v[28:29], 1.0 op_sel_hi:[1,0]
	v_pk_add_f32 v[24:25], v[26:27], 1.0 op_sel_hi:[1,0]
	v_pk_mul_f32 v[20:21], v[20:21], v[30:31]
	v_pk_mul_f32 v[4:5], v[4:5], v[32:33]
	v_pk_add_f32 v[26:27], v[36:37], 1.0 op_sel_hi:[1,0]
	v_pk_add_f32 v[28:29], v[34:35], 1.0 op_sel_hi:[1,0]
	v_pk_fma_f32 v[2:3], v[2:3], v[22:23], v[40:41]
	v_pk_fma_f32 v[18:19], v[18:19], v[24:25], v[38:39]
	v_pk_fma_f32 v[4:5], v[4:5], v[26:27], v[44:45]
	v_pk_fma_f32 v[20:21], v[20:21], v[28:29], v[42:43]
	v_bfe_u32 v22, v18, 16, 1
	v_bfe_u32 v24, v2, 16, 1
	v_bfe_u32 v26, v20, 16, 1
	v_bfe_u32 v28, v4, 16, 1
	v_bfe_u32 v23, v19, 16, 1
	v_bfe_u32 v25, v3, 16, 1
	v_bfe_u32 v27, v21, 16, 1
	v_bfe_u32 v29, v5, 16, 1
	v_add3_u32 v18, v18, v22, s27
	v_add3_u32 v2, v2, v24, s27
	v_add3_u32 v20, v20, v26, s27
	v_add3_u32 v4, v4, v28, s27
	v_add3_u32 v19, v19, v23, s27
	v_add3_u32 v3, v3, v25, s27
	v_add3_u32 v21, v21, v27, s27
	v_add3_u32 v5, v5, v29, s27
	v_lshrrev_b32_e32 v18, 16, v18
	v_lshrrev_b32_e32 v22, 16, v2
	v_lshrrev_b32_e32 v20, 16, v20
	v_lshrrev_b32_e32 v23, 16, v4
	v_and_or_b32 v2, v19, s25, v18
	v_and_or_b32 v3, v3, s25, v22
	v_and_or_b32 v4, v21, s25, v20
	v_and_or_b32 v5, v5, s25, v23
	global_store_dwordx4 v[70:71], v[2:5], off offset:3072
	s_branch .LBB0_678

; __device__ __forceinline__ void unpack8(const v4u& w, float (&f)[8]) { f[0] = bflo(w.x); f[1] = bfhi(w.x); f[2] = bflo(w.y); f[3] = bfhi(w.y); f[4] = bflo(w.z); f[5] = bfhi(w.z); f[6] = bflo(w.w); f[7] = bfhi(w.w); }
; template <bool ZP, bool XF32, bool OUT8 = false>
; __device__ __forceinline__ void norm_phase(LAS unsigned char* lds, const void* xin, const float* gain, const float* sh, const float* sc, bf16* hout, const float* wzt, float* zout, int lane, int wave, int vcu, int G) {
;     ...
;     for (int it_ = 0; it_ < nit; ++it_) {
;         const int m0 = xdeal ? 2048 * (gw >> 8) + 2 * (gw & 255) + 512 * it_ : 2 * gw + it_ * 2 * NGW;
;         if (m0 >= M) break;
;         f32x4 v[2][4][2]; float ss[2] = {0.f, 0.f};
; #pragma unroll
;         for (int r = 0; r < 2; ++r)
; #pragma unroll
;             for (int j = 0; j < 4; ++j) {
;                 if constexpr (XF32) { const float* xr = (const float*)xin + (size_t)(m0 + r) * D + 8 * lane; v[r][j][0] = *(const f32x4*)(xr + 512 * j); v[r][j][1] = *(const f32x4*)(xr + 512 * j + 4); }
;                 else { float f[8]; unpack8(*(const v4u*)((const bf16*)xin + (size_t)(m0 + r) * D + 8 * lane + 512 * j), f); v[r][j][0] = (f32x4){f[0], f[1], f[2], f[3]}; v[r][j][1] = (f32x4){f[4], f[5], f[6], f[7]}; } }
; #pragma unroll
;         for (int r = 0; r < 2; ++r)
; #pragma unroll
;             for (int j = 0; j < 4; ++j)
; #pragma unroll
;                 for (int e = 0; e < 4; ++e) ss[r] += v[r][j][0][e] * v[r][j][0][e] + v[r][j][1][e] * v[r][j][1][e];
; #pragma unroll
;         for (int r = 0; r < 2; ++r) { const int m = m0 + r, b = m >> 11;
;             const float rstd = rsqrtf(wave_sum(ss[r]) * (1.0f / D) + EPS);
; #pragma unroll
;             for (int j = 0; j < 4; ++j) { const int col = 512 * j + 8 * lane;
; #pragma unroll
;                 for (int q = 0; q < 2; ++q) { const f32x4 gg = *(const f32x4*)(gain + col + 4 * q), s1 = *(const f32x4*)(sc + (size_t)b * MODW + col + 4 * q), s0 = *(const f32x4*)(sh + (size_t)b * MODW + col + 4 * q);
;                     v[r][j][q] = (v[r][j][q] * rstd * gg) * (s1 + 1.0f) + s0; }
.LBB0_940:
	s_ashr_i32 s15, s14, 31
	s_add_i32 s10, s14, 1
	s_lshl_b64 s[12:13], s[14:15], 12
	s_ashr_i32 s11, s10, 31
	v_lshl_add_u64 v[2:3], v[6:7], 0, s[12:13]
	v_lshl_add_u64 v[244:245], v[2:3], 0, s[100:101]
	s_lshl_b64 s[8:9], s[10:11], 12
	global_load_dwordx4 v[20:23], v[2:3], off offset:1024
	global_load_dwordx4 v[24:27], v[2:3], off offset:3072
	global_load_dwordx4 v[34:37], v[2:3], off
	global_load_dwordx4 v[40:43], v[2:3], off offset:2048
	v_lshl_add_u64 v[28:29], v[6:7], 0, s[8:9]
	v_lshl_add_u64 v[246:247], v[28:29], 0, s[100:101]
	global_load_dwordx4 v[80:83], v[28:29], off offset:1024
	global_load_dwordx4 v[94:97], v[28:29], off
	global_load_dwordx4 v[2:5], v[28:29], off offset:3072
	global_load_dwordx4 v[98:101], v[28:29], off offset:2048
	s_ashr_i32 s0, s14, 11
	s_mul_hi_i32 s1, s0, 0xc000
	s_mul_i32 s0, s0, 0xc000
	s_add_u32 s14, s19, s0
	s_addc_u32 s15, s20, s1
	s_add_u32 s16, s7, s0
	s_addc_u32 s17, s18, s1
	v_cmp_lt_i32_e32 vcc, v88, v87
	s_ashr_i32 s0, s10, 11
	s_mul_hi_i32 s1, s0, 0xc000
	v_cndmask_b32_e32 v84, v86, v88, vcc
	v_lshlrev_b32_e32 v84, 2, v84
	v_cmp_lt_i32_e32 vcc, v89, v87
	s_mul_i32 s0, s0, 0xc000
	s_add_u32 s10, s19, s0
	s_addc_u32 s11, s20, s1
	s_waitcnt vmcnt(0)
	v_lshlrev_b32_e32 v47, 16, v22
	v_lshlrev_b32_e32 v45, 16, v20
	v_lshlrev_b32_e32 v59, 16, v36
	v_and_b32_e32 v63, 0xffff0000, v36
	v_lshlrev_b32_e32 v58, 16, v96
	v_and_b32_e32 v62, 0xffff0000, v96
	v_lshlrev_b32_e32 v57, 16, v34
	v_and_b32_e32 v61, 0xffff0000, v34
	v_lshlrev_b32_e32 v65, 16, v37
	v_and_b32_e32 v28, 0xffff0000, v80
	v_and_b32_e32 v32, 0xffff0000, v82
	v_lshlrev_b32_e32 v56, 16, v94
	v_and_b32_e32 v60, 0xffff0000, v94
	v_lshlrev_b32_e32 v64, 16, v97
	v_lshlrev_b32_e32 v44, 16, v80
	v_lshlrev_b32_e32 v46, 16, v82
	v_lshlrev_b32_e32 v48, 16, v81
	v_and_b32_e32 v50, 0xffff0000, v81
	v_lshlrev_b32_e32 v52, 16, v83
	v_and_b32_e32 v54, 0xffff0000, v83
	v_pk_mul_f32 v[80:81], v[58:59], v[58:59]
	v_pk_mul_f32 v[82:83], v[62:63], v[62:63]
	v_lshlrev_b32_e32 v67, 16, v35
	v_and_b32_e32 v71, 0xffff0000, v37
	v_lshlrev_b32_e32 v66, 16, v95
	v_and_b32_e32 v68, 0xffff0000, v95
	v_and_b32_e32 v70, 0xffff0000, v97
	v_pk_mul_f32 v[94:95], v[64:65], v[64:65]
	v_pk_fma_f32 v[80:81], v[56:57], v[56:57], v[80:81]
	v_pk_fma_f32 v[82:83], v[60:61], v[60:61], v[82:83]
	v_and_b32_e32 v69, 0xffff0000, v35
	v_pk_mul_f32 v[96:97], v[70:71], v[70:71]
	v_pk_fma_f32 v[94:95], v[66:67], v[66:67], v[94:95]
	v_pk_add_f32 v[80:81], v[80:81], v[82:83]
	v_pk_fma_f32 v[82:83], v[68:69], v[68:69], v[96:97]
	v_pk_add_f32 v[80:81], v[94:95], v[80:81]
	v_and_b32_e32 v33, 0xffff0000, v22
	v_pk_add_f32 v[80:81], v[82:83], v[80:81]
	v_pk_mul_f32 v[82:83], v[46:47], v[46:47]
	v_and_b32_e32 v29, 0xffff0000, v20
	v_pk_fma_f32 v[82:83], v[44:45], v[44:45], v[82:83]
	v_lshlrev_b32_e32 v53, 16, v23
	v_pk_add_f32 v[80:81], v[82:83], v[80:81]
	v_pk_mul_f32 v[82:83], v[32:33], v[32:33]
	v_lshlrev_b32_e32 v49, 16, v21
	v_pk_fma_f32 v[82:83], v[28:29], v[28:29], v[82:83]
	v_and_b32_e32 v51, 0xffff0000, v21
	v_and_b32_e32 v20, 0xffff0000, v4
	v_lshlrev_b32_e32 v21, 16, v4
	v_pk_add_f32 v[80:81], v[82:83], v[80:81]
	v_pk_mul_f32 v[82:83], v[52:53], v[52:53]
	v_and_b32_e32 v72, 0xffff0000, v24
	v_lshlrev_b32_e32 v73, 16, v24
	v_and_b32_e32 v74, 0xffff0000, v26
	v_lshlrev_b32_e32 v75, 16, v26
	v_and_b32_e32 v55, 0xffff0000, v23
	v_and_b32_e32 v22, 0xffff0000, v2
	v_lshlrev_b32_e32 v23, 16, v2
	v_lshlrev_b32_e32 v24, 16, v98
	v_and_b32_e32 v26, 0xffff0000, v98
	v_lshlrev_b32_e32 v30, 16, v99
	v_and_b32_e32 v34, 0xffff0000, v99
	v_pk_mul_f32 v[98:99], v[20:21], v[20:21]
	v_pk_fma_f32 v[82:83], v[48:49], v[48:49], v[82:83]
	v_pk_fma_f32 v[118:119], v[22:23], v[22:23], v[98:99]
	v_pk_add_f32 v[98:99], v[82:83], v[80:81]
	global_load_dwordx4 v[128:131], v1, s[14:15] offset:16
	global_load_dwordx4 v[132:135], v1, s[14:15]
	global_load_dwordx4 v[136:139], v[8:9], off offset:16
	global_load_dwordx4 v[140:143], v[8:9], off
	global_load_dwordx4 v[144:147], v1, s[16:17] offset:16
	global_load_dwordx4 v[148:151], v1, s[16:17]
	global_load_dwordx4 v[152:155], v[10:11], off
	global_load_dwordx4 v[156:159], v1, s[14:15] offset:2048
	global_load_dwordx4 v[160:163], v1, s[16:17] offset:2048
	global_load_dwordx4 v[164:167], v[10:11], off offset:16
	global_load_dwordx4 v[168:171], v1, s[14:15] offset:2064
	global_load_dwordx4 v[172:175], v1, s[16:17] offset:2064
	global_load_dwordx4 v[176:179], v[12:13], off
	global_load_dwordx4 v[180:183], v19, s[14:15]
	global_load_dwordx4 v[184:187], v[12:13], off offset:16
	global_load_dwordx4 v[188:191], v19, s[14:15] offset:16
	global_load_dwordx4 v[192:195], v19, s[16:17]
	global_load_dwordx4 v[196:199], v19, s[16:17] offset:16
	global_load_dwordx4 v[200:203], v[14:15], off
	global_load_dwordx4 v[204:207], v85, s[14:15]
	global_load_dwordx4 v[208:211], v[14:15], off offset:16
	global_load_dwordx4 v[212:215], v85, s[14:15] offset:16
	global_load_dwordx4 v[216:219], v85, s[16:17]
	global_load_dwordx4 v[220:223], v85, s[16:17] offset:16
	v_and_b32_e32 v76, 0xffff0000, v25
	v_lshlrev_b32_e32 v77, 16, v25
	v_and_b32_e32 v78, 0xffff0000, v27
	v_lshlrev_b32_e32 v79, 16, v27
	v_lshlrev_b32_e32 v25, 16, v40
	v_and_b32_e32 v27, 0xffff0000, v40
	v_lshlrev_b32_e32 v37, 16, v42
	v_and_b32_e32 v39, 0xffff0000, v42
	v_lshlrev_b32_e32 v36, 16, v100
	v_and_b32_e32 v38, 0xffff0000, v100
	v_lshlrev_b32_e32 v40, 16, v101
	v_and_b32_e32 v42, 0xffff0000, v101
	v_pk_mul_f32 v[100:101], v[54:55], v[54:55]
	v_lshlrev_b32_e32 v31, 16, v41
	v_pk_fma_f32 v[100:101], v[50:51], v[50:51], v[100:101]
	v_and_b32_e32 v35, 0xffff0000, v41
	v_pk_add_f32 v[98:99], v[100:101], v[98:99]
; __device__ __forceinline__ unsigned pk2(float lo, float hi) { return f2bf(lo) | (f2bf(hi) << 16); }
; template <bool ZP, bool XF32, bool OUT8 = false>
; __device__ __forceinline__ void norm_phase(LAS unsigned char* lds, const void* xin, const float* gain, const float* sh, const float* sc, bf16* hout, const float* wzt, float* zout, int lane, int wave, int vcu, int G) {
;     ...
;                 for (int e = 0; e < 4; ++e) ss[r] += v[r][j][0][e] * v[r][j][0][e] + v[r][j][1][e] * v[r][j][1][e];
; #pragma unroll
;         for (int r = 0; r < 2; ++r) { const int m = m0 + r, b = m >> 11;
;             const float rstd = rsqrtf(wave_sum(ss[r]) * (1.0f / D) + EPS);
; #pragma unroll
;             for (int j = 0; j < 4; ++j) { const int col = 512 * j + 8 * lane;
; #pragma unroll
;                 for (int q = 0; q < 2; ++q) { const f32x4 gg = *(const f32x4*)(gain + col + 4 * q), s1 = *(const f32x4*)(sc + (size_t)b * MODW + col + 4 * q), s0 = *(const f32x4*)(sh + (size_t)b * MODW + col + 4 * q);
;                     v[r][j][q] = (v[r][j][q] * rstd * gg) * (s1 + 1.0f) + s0; }
;                 if constexpr (OUT8) { *(v2u*)((unsigned char*)hout + (size_t)m * D + col) = pack8_fp8(v[r][j][0][0], v[r][j][0][1], v[r][j][0][2], v[r][j][0][3], v[r][j][1][0], v[r][j][1][1], v[r][j][1][2], v[r][j][1][3], FP8_ASCALE); }
;                 else { v4u o; o.x = pk2(v[r][j][0][0], v[r][j][0][1]); o.y = pk2(v[r][j][0][2], v[r][j][0][3]); o.z = pk2(v[r][j][1][0], v[r][j][1][1]); o.w = pk2(v[r][j][1][2], v[r][j][1][3]);
;                     *(v4u*)(hout + (size_t)m * D + col) = o; } }
	v_pk_mul_f32 v[100:101], v[36:37], v[36:37]
	v_lshlrev_b32_e32 v41, 16, v43
	v_pk_fma_f32 v[100:101], v[24:25], v[24:25], v[100:101]
	v_and_b32_e32 v43, 0xffff0000, v43
	v_pk_add_f32 v[98:99], v[100:101], v[98:99]
	v_pk_mul_f32 v[100:101], v[38:39], v[38:39]
	v_pk_mul_f32 v[102:103], v[74:75], v[74:75]
	v_pk_fma_f32 v[100:101], v[26:27], v[26:27], v[100:101]
	v_pk_mul_f32 v[104:105], v[78:79], v[78:79]
	v_pk_add_f32 v[98:99], v[100:101], v[98:99]
	v_pk_mul_f32 v[100:101], v[40:41], v[40:41]
	v_pk_fma_f32 v[114:115], v[72:73], v[72:73], v[102:103]
	v_pk_fma_f32 v[100:101], v[30:31], v[30:31], v[100:101]
	v_pk_fma_f32 v[116:117], v[76:77], v[76:77], v[104:105]
	v_pk_add_f32 v[98:99], v[100:101], v[98:99]
	v_pk_mul_f32 v[100:101], v[42:43], v[42:43]
	v_mov_b32_e32 v122, v119
	v_pk_fma_f32 v[100:101], v[34:35], v[34:35], v[100:101]
	v_mov_b32_e32 v123, v115
	v_pk_add_f32 v[120:121], v[100:101], v[98:99]
	v_and_b32_e32 v4, 0xffff0000, v5
	v_lshlrev_b32_e32 v5, 16, v5
	v_pk_add_f32 v[120:121], v[122:123], v[120:121]
	v_and_b32_e32 v2, 0xffff0000, v3
	v_lshlrev_b32_e32 v3, 16, v3
	v_pk_mul_f32 v[122:123], v[4:5], v[4:5]
	v_mov_b32_e32 v119, v114
	v_pk_fma_f32 v[122:123], v[2:3], v[2:3], v[122:123]
	v_pk_add_f32 v[114:115], v[118:119], v[120:121]
	v_mov_b32_e32 v118, v123
	v_mov_b32_e32 v119, v117
	v_pk_add_f32 v[114:115], v[118:119], v[114:115]
	v_mov_b32_e32 v123, v116
	v_pk_add_f32 v[114:115], v[122:123], v[114:115]
	ds_bpermute_b32 v117, v84, v115
	ds_bpermute_b32 v116, v84, v114
	v_cndmask_b32_e32 v84, v86, v89, vcc
	v_lshlrev_b32_e32 v84, 2, v84
	v_cmp_lt_i32_e32 vcc, v90, v87
	v_mov_b32_e32 v124, v37
	s_waitcnt lgkmcnt(0)
	v_pk_add_f32 v[114:115], v[114:115], v[116:117]
	ds_bpermute_b32 v117, v84, v115
	ds_bpermute_b32 v116, v84, v114
	v_cndmask_b32_e32 v84, v86, v90, vcc
	v_lshlrev_b32_e32 v84, 2, v84
	v_cmp_lt_i32_e32 vcc, v91, v87
	v_mov_b32_e32 v125, v39
	s_waitcnt lgkmcnt(0)
	v_pk_add_f32 v[114:115], v[114:115], v[116:117]
	ds_bpermute_b32 v117, v84, v115
	ds_bpermute_b32 v116, v84, v114
	v_cndmask_b32_e32 v84, v86, v91, vcc
	v_lshlrev_b32_e32 v84, 2, v84
	v_cmp_lt_i32_e32 vcc, v92, v87
	v_mov_b32_e32 v122, v41
	s_waitcnt lgkmcnt(0)
	v_pk_add_f32 v[114:115], v[114:115], v[116:117]
	ds_bpermute_b32 v117, v84, v115
	ds_bpermute_b32 v116, v84, v114
	v_cndmask_b32_e32 v84, v86, v92, vcc
	v_lshlrev_b32_e32 v84, 2, v84
	v_cmp_lt_i32_e32 vcc, v93, v87
	s_waitcnt vmcnt(0)
	v_mov_b64_e32 v[94:95], v[128:129]
	v_mov_b64_e32 v[96:97], v[130:131]
	v_mov_b64_e32 v[80:81], v[132:133]
	v_mov_b64_e32 v[82:83], v[134:135]
	v_mov_b64_e32 v[98:99], v[136:137]
	v_mov_b64_e32 v[100:101], v[138:139]
	v_mov_b64_e32 v[102:103], v[140:141]
	v_mov_b64_e32 v[104:105], v[142:143]
	v_mov_b64_e32 v[106:107], v[144:145]
	v_mov_b64_e32 v[108:109], v[146:147]
	v_mov_b64_e32 v[110:111], v[148:149]
	v_mov_b64_e32 v[112:113], v[150:151]
	global_load_dwordx4 v[248:251], v[244:245], off offset:1024
	global_load_dwordx4 v[248:251], v[244:245], off offset:3072
	global_load_dwordx4 v[248:251], v[244:245], off
	global_load_dwordx4 v[248:251], v[244:245], off offset:2048
	global_load_dwordx4 v[248:251], v[246:247], off offset:1024
	global_load_dwordx4 v[248:251], v[246:247], off
	global_load_dwordx4 v[248:251], v[246:247], off offset:3072
	global_load_dwordx4 v[248:251], v[246:247], off offset:2048
	v_pk_add_f32 v[96:97], v[96:97], 1.0 op_sel_hi:[1,0]
	s_waitcnt lgkmcnt(0)
	v_pk_add_f32 v[114:115], v[114:115], v[116:117]
	ds_bpermute_b32 v117, v84, v115
	ds_bpermute_b32 v116, v84, v114
	v_cndmask_b32_e32 v84, v86, v93, vcc
	v_lshlrev_b32_e32 v84, 2, v84
	v_pk_add_f32 v[120:121], v[80:81], 1.0 op_sel_hi:[1,0]
	v_pk_add_f32 v[118:119], v[82:83], 1.0 op_sel_hi:[1,0]
	s_waitcnt lgkmcnt(0)
	v_pk_add_f32 v[114:115], v[114:115], v[116:117]
	ds_bpermute_b32 v117, v84, v115
	ds_bpermute_b32 v116, v84, v114
	v_pk_add_f32 v[94:95], v[94:95], 1.0 op_sel_hi:[1,0]
	v_mov_b32_e32 v123, v43
	v_pk_mov_b32 v[76:77], v[76:77], v[76:77] op_sel:[1,0]
	v_pk_mov_b32 v[78:79], v[78:79], v[78:79] op_sel:[1,0]
	s_waitcnt lgkmcnt(0)
	v_pk_add_f32 v[80:81], v[114:115], v[116:117]
	v_mov_b32_e32 v116, v57
	v_pk_fma_f32 v[80:81], v[80:81], s[6:7], v[18:19] op_sel_hi:[1,0,0]
	v_mov_b32_e32 v117, v61
	v_mul_f32_e32 v82, 0x4b800000, v81
	v_cmp_gt_f32_e32 vcc, s26, v81
	v_mov_b32_e32 v114, v67
	v_mov_b32_e32 v115, v69
	v_cndmask_b32_e32 v81, v81, v82, vcc
	v_rsq_f32_e32 v81, v81
	v_lshl_add_u64 v[82:83], v[16:17], 0, s[12:13]
	s_add_u32 s12, s7, s0
	s_addc_u32 s13, s18, s1
	v_mul_f32_e32 v84, 0x45800000, v81
	v_cndmask_b32_e32 v84, v81, v84, vcc
	v_pk_mul_f32 v[116:117], v[84:85], v[116:117] op_sel_hi:[0,1]
	v_pk_mul_f32 v[114:115], v[84:85], v[114:115] op_sel_hi:[0,1]
	v_pk_mul_f32 v[124:125], v[84:85], v[124:125] op_sel_hi:[0,1]
	v_pk_mul_f32 v[122:123], v[84:85], v[122:123] op_sel_hi:[0,1]
	v_pk_mul_f32 v[78:79], v[84:85], v[78:79] op_sel_hi:[0,1]
	v_cmp_gt_f32_e32 vcc, s26, v80
	v_mov_b32_e32 v67, v68
	v_pk_mul_f32 v[102:103], v[102:103], v[116:117]
	v_pk_mul_f32 v[104:105], v[104:105], v[114:115]
	v_pk_fma_f32 v[102:103], v[120:121], v[102:103], v[110:111]
	v_pk_fma_f32 v[104:105], v[118:119], v[104:105], v[112:113]
	v_mov_b32_e32 v110, v65
	v_mov_b32_e32 v111, v71
	v_mov_b32_e32 v112, v59
	v_mov_b32_e32 v113, v63
	v_bfe_u32 v57, v102, 16, 1
	v_pk_mul_f32 v[110:111], v[84:85], v[110:111] op_sel_hi:[0,1]
	v_pk_mul_f32 v[112:113], v[84:85], v[112:113] op_sel_hi:[0,1]
	v_add3_u32 v57, v102, v57, s27
	v_bfe_u32 v59, v103, 16, 1
	v_pk_mul_f32 v[98:99], v[98:99], v[112:113]
	v_pk_mul_f32 v[100:101], v[100:101], v[110:111]
	v_lshrrev_b32_e32 v57, 16, v57
	v_add3_u32 v59, v103, v59, s27
; __device__ __forceinline__ unsigned pk2(float lo, float hi) { return f2bf(lo) | (f2bf(hi) << 16); }
; template <bool ZP, bool XF32, bool OUT8 = false>
; __device__ __forceinline__ void norm_phase(LAS unsigned char* lds, const void* xin, const float* gain, const float* sh, const float* sc, bf16* hout, const float* wzt, float* zout, int lane, int wave, int vcu, int G) {
;     ...
;         for (int r = 0; r < 2; ++r) { const int m = m0 + r, b = m >> 11;
;             const float rstd = rsqrtf(wave_sum(ss[r]) * (1.0f / D) + EPS);
; #pragma unroll
;             for (int j = 0; j < 4; ++j) { const int col = 512 * j + 8 * lane;
; #pragma unroll
;                 for (int q = 0; q < 2; ++q) { const f32x4 gg = *(const f32x4*)(gain + col + 4 * q), s1 = *(const f32x4*)(sc + (size_t)b * MODW + col + 4 * q), s0 = *(const f32x4*)(sh + (size_t)b * MODW + col + 4 * q);
;                     v[r][j][q] = (v[r][j][q] * rstd * gg) * (s1 + 1.0f) + s0; }
;                 if constexpr (OUT8) { *(v2u*)((unsigned char*)hout + (size_t)m * D + col) = pack8_fp8(v[r][j][0][0], v[r][j][0][1], v[r][j][0][2], v[r][j][0][3], v[r][j][1][0], v[r][j][1][1], v[r][j][1][2], v[r][j][1][3], FP8_ASCALE); }
;                 else { v4u o; o.x = pk2(v[r][j][0][0], v[r][j][0][1]); o.y = pk2(v[r][j][0][2], v[r][j][0][3]); o.z = pk2(v[r][j][1][0], v[r][j][1][1]); o.w = pk2(v[r][j][1][2], v[r][j][1][3]);
;                     *(v4u*)(hout + (size_t)m * D + col) = o; } }
	v_pk_fma_f32 v[100:101], v[96:97], v[100:101], v[108:109]
	v_pk_fma_f32 v[96:97], v[94:95], v[98:99], v[106:107]
	v_and_or_b32 v94, v59, s25, v57
	v_bfe_u32 v57, v104, 16, 1
	v_add3_u32 v57, v104, v57, s27
	v_bfe_u32 v59, v105, 16, 1
	v_lshrrev_b32_e32 v57, 16, v57
	v_add3_u32 v59, v105, v59, s27
	v_and_or_b32 v95, v59, s25, v57
	v_bfe_u32 v57, v96, 16, 1
	v_add3_u32 v57, v96, v57, s27
	v_bfe_u32 v59, v97, 16, 1
	v_lshrrev_b32_e32 v57, 16, v57
	v_add3_u32 v59, v97, v59, s27
	v_and_or_b32 v96, v59, s25, v57
	v_bfe_u32 v57, v100, 16, 1
	v_add3_u32 v57, v100, v57, s27
	v_bfe_u32 v59, v101, 16, 1
	v_lshrrev_b32_e32 v57, 16, v57
	v_add3_u32 v59, v101, v59, s27
	v_and_or_b32 v97, v59, s25, v57
	global_store_dwordx4 v[82:83], v[94:97], off
	s_nop 1
	v_mov_b64_e32 v[94:95], v[152:153]
	v_mov_b64_e32 v[96:97], v[154:155]
	s_nop 0
	s_nop 1
	v_mov_b64_e32 v[98:99], v[156:157]
	v_mov_b64_e32 v[100:101], v[158:159]
	v_mov_b64_e32 v[102:103], v[160:161]
	v_mov_b64_e32 v[104:105], v[162:163]
	v_mov_b64_e32 v[106:107], v[164:165]
	v_mov_b64_e32 v[108:109], v[166:167]
	v_mov_b64_e32 v[110:111], v[168:169]
	v_mov_b64_e32 v[112:113], v[170:171]
	v_mov_b64_e32 v[114:115], v[172:173]
	v_mov_b64_e32 v[116:117], v[174:175]
	v_mov_b32_e32 v120, v45
	v_mov_b32_e32 v121, v29
	v_pk_mul_f32 v[120:121], v[84:85], v[120:121] op_sel_hi:[0,1]
	v_mov_b32_e32 v118, v49
	v_mov_b32_e32 v119, v51
	v_pk_mul_f32 v[118:119], v[84:85], v[118:119] op_sel_hi:[0,1]
	v_mov_b32_e32 v65, v70
	v_mov_b32_e32 v59, v62
	v_mov_b32_e32 v57, v60
	v_mov_b32_e32 v49, v50
	v_mov_b32_e32 v45, v28
	v_pk_mov_b32 v[2:3], v[2:3], v[2:3] op_sel:[1,0]
	v_pk_mov_b32 v[4:5], v[4:5], v[4:5] op_sel:[1,0]
	s_add_i32 s24, s24, 1
	s_addk_i32 s23, 0x200
	s_add_i32 s3, s3, -1
	s_cmp_eq_u32 s3, 0
	v_pk_mul_f32 v[94:95], v[94:95], v[120:121]
	v_pk_add_f32 v[98:99], v[98:99], 1.0 op_sel_hi:[1,0]
	v_pk_mul_f32 v[96:97], v[96:97], v[118:119]
	v_pk_fma_f32 v[94:95], v[98:99], v[94:95], v[102:103]
	v_pk_add_f32 v[100:101], v[100:101], 1.0 op_sel_hi:[1,0]
	v_bfe_u32 v29, v94, 16, 1
	v_pk_fma_f32 v[96:97], v[100:101], v[96:97], v[104:105]
	v_mov_b32_e32 v101, v33
	v_add3_u32 v29, v94, v29, s27
	v_bfe_u32 v33, v95, 16, 1
	v_mov_b32_e32 v100, v47
	v_lshrrev_b32_e32 v29, 16, v29
	v_add3_u32 v33, v95, v33, s27
	v_pk_mul_f32 v[100:101], v[84:85], v[100:101] op_sel_hi:[0,1]
	v_and_or_b32 v94, v33, s25, v29
	v_bfe_u32 v29, v96, 16, 1
	v_pk_mul_f32 v[100:101], v[106:107], v[100:101]
	v_pk_add_f32 v[104:105], v[110:111], 1.0 op_sel_hi:[1,0]
	v_add3_u32 v29, v96, v29, s27
	v_bfe_u32 v33, v97, 16, 1
	v_mov_b32_e32 v98, v53
	v_mov_b32_e32 v99, v55
	v_pk_fma_f32 v[100:101], v[104:105], v[100:101], v[114:115]
	v_lshrrev_b32_e32 v29, 16, v29
	v_add3_u32 v33, v97, v33, s27
	v_pk_mul_f32 v[98:99], v[84:85], v[98:99] op_sel_hi:[0,1]
	v_and_or_b32 v95, v33, s25, v29
	v_bfe_u32 v29, v100, 16, 1
	v_pk_mul_f32 v[98:99], v[108:109], v[98:99]
	v_pk_add_f32 v[102:103], v[112:113], 1.0 op_sel_hi:[1,0]
	v_add3_u32 v29, v100, v29, s27
	v_bfe_u32 v33, v101, 16, 1
	v_pk_fma_f32 v[98:99], v[102:103], v[98:99], v[116:117]
	v_lshrrev_b32_e32 v29, 16, v29
	v_add3_u32 v33, v101, v33, s27
	v_and_or_b32 v96, v33, s25, v29
	v_bfe_u32 v29, v98, 16, 1
	v_add3_u32 v29, v98, v29, s27
	v_bfe_u32 v33, v99, 16, 1
	v_lshrrev_b32_e32 v29, 16, v29
	v_add3_u32 v33, v99, v33, s27
	v_and_or_b32 v97, v33, s25, v29
	global_store_dwordx4 v[82:83], v[94:97], off offset:1024
	s_nop 1
	v_mov_b64_e32 v[94:95], v[176:177]
	v_mov_b64_e32 v[96:97], v[178:179]
	s_nop 0
	s_nop 1
	v_mov_b64_e32 v[98:99], v[180:181]
	v_mov_b64_e32 v[100:101], v[182:183]
	v_mov_b64_e32 v[102:103], v[184:185]
	v_mov_b64_e32 v[104:105], v[186:187]
	v_mov_b64_e32 v[106:107], v[188:189]
	v_mov_b64_e32 v[108:109], v[190:191]
	v_mov_b64_e32 v[110:111], v[192:193]
	v_mov_b64_e32 v[112:113], v[194:195]
	v_mov_b64_e32 v[114:115], v[196:197]
	v_mov_b64_e32 v[116:117], v[198:199]
	v_mov_b32_e32 v120, v25
	v_mov_b32_e32 v121, v27
	v_pk_mul_f32 v[120:121], v[84:85], v[120:121] op_sel_hi:[0,1]
	v_mov_b32_e32 v118, v31
	v_mov_b32_e32 v119, v35
	v_pk_mul_f32 v[118:119], v[84:85], v[118:119] op_sel_hi:[0,1]
	v_mov_b32_e32 v53, v54
	v_mov_b32_e32 v47, v32
	v_pk_mul_f32 v[94:95], v[94:95], v[120:121]
	v_pk_add_f32 v[98:99], v[98:99], 1.0 op_sel_hi:[1,0]
	v_pk_mul_f32 v[96:97], v[96:97], v[118:119]
	v_pk_add_f32 v[100:101], v[100:101], 1.0 op_sel_hi:[1,0]
	v_pk_fma_f32 v[94:95], v[98:99], v[94:95], v[110:111]
	v_pk_fma_f32 v[96:97], v[100:101], v[96:97], v[112:113]
	v_bfe_u32 v25, v94, 16, 1
	v_bfe_u32 v27, v95, 16, 1
	v_add3_u32 v25, v94, v25, s27
	v_lshrrev_b32_e32 v25, 16, v25
	v_add3_u32 v27, v95, v27, s27
	v_and_or_b32 v94, v27, s25, v25
	v_bfe_u32 v25, v96, 16, 1
	v_pk_mul_f32 v[102:103], v[102:103], v[124:125]
	v_pk_add_f32 v[106:107], v[106:107], 1.0 op_sel_hi:[1,0]
	v_add3_u32 v25, v96, v25, s27
	v_bfe_u32 v27, v97, 16, 1
	v_pk_fma_f32 v[100:101], v[106:107], v[102:103], v[114:115]
	v_lshrrev_b32_e32 v25, 16, v25
	v_add3_u32 v27, v97, v27, s27
	v_and_or_b32 v95, v27, s25, v25
	v_bfe_u32 v25, v100, 16, 1
	v_pk_mul_f32 v[104:105], v[104:105], v[122:123]
	v_pk_add_f32 v[108:109], v[108:109], 1.0 op_sel_hi:[1,0]
	v_add3_u32 v25, v100, v25, s27
	v_bfe_u32 v27, v101, 16, 1
	v_pk_fma_f32 v[98:99], v[108:109], v[104:105], v[116:117]
	v_lshrrev_b32_e32 v25, 16, v25
	v_add3_u32 v27, v101, v27, s27
	v_and_or_b32 v96, v27, s25, v25
	v_bfe_u32 v25, v98, 16, 1
	v_add3_u32 v25, v98, v25, s27
	v_bfe_u32 v27, v99, 16, 1
	v_lshrrev_b32_e32 v25, 16, v25
	v_add3_u32 v27, v99, v27, s27
	v_and_or_b32 v97, v27, s25, v25
	global_store_dwordx4 v[82:83], v[94:97], off offset:2048
	s_nop 1
	v_mov_b64_e32 v[94:95], v[200:201]
; __device__ __forceinline__ unsigned pk2(float lo, float hi) { return f2bf(lo) | (f2bf(hi) << 16); }
; template <bool ZP, bool XF32, bool OUT8 = false>
; __device__ __forceinline__ void norm_phase(LAS unsigned char* lds, const void* xin, const float* gain, const float* sh, const float* sc, bf16* hout, const float* wzt, float* zout, int lane, int wave, int vcu, int G) {
;     ...
;         for (int r = 0; r < 2; ++r) { const int m = m0 + r, b = m >> 11;
;             const float rstd = rsqrtf(wave_sum(ss[r]) * (1.0f / D) + EPS);
; #pragma unroll
;             for (int j = 0; j < 4; ++j) { const int col = 512 * j + 8 * lane;
; #pragma unroll
;                 for (int q = 0; q < 2; ++q) { const f32x4 gg = *(const f32x4*)(gain + col + 4 * q), s1 = *(const f32x4*)(sc + (size_t)b * MODW + col + 4 * q), s0 = *(const f32x4*)(sh + (size_t)b * MODW + col + 4 * q);
;                     v[r][j][q] = (v[r][j][q] * rstd * gg) * (s1 + 1.0f) + s0; }
;                 if constexpr (OUT8) { *(v2u*)((unsigned char*)hout + (size_t)m * D + col) = pack8_fp8(v[r][j][0][0], v[r][j][0][1], v[r][j][0][2], v[r][j][0][3], v[r][j][1][0], v[r][j][1][1], v[r][j][1][2], v[r][j][1][3], FP8_ASCALE); }
;                 else { v4u o; o.x = pk2(v[r][j][0][0], v[r][j][0][1]); o.y = pk2(v[r][j][0][2], v[r][j][0][3]); o.z = pk2(v[r][j][1][0], v[r][j][1][1]); o.w = pk2(v[r][j][1][2], v[r][j][1][3]);
;                     *(v4u*)(hout + (size_t)m * D + col) = o; } }
	v_mov_b64_e32 v[96:97], v[202:203]
	s_nop 0
	s_nop 1
	v_mov_b64_e32 v[98:99], v[204:205]
	v_mov_b64_e32 v[100:101], v[206:207]
	v_mov_b64_e32 v[102:103], v[208:209]
	v_mov_b64_e32 v[104:105], v[210:211]
	v_mov_b64_e32 v[106:107], v[212:213]
	v_mov_b64_e32 v[108:109], v[214:215]
	v_mov_b64_e32 v[110:111], v[216:217]
	v_mov_b64_e32 v[112:113], v[218:219]
	v_mov_b64_e32 v[114:115], v[220:221]
	v_mov_b64_e32 v[116:117], v[222:223]
	v_mov_b32_e32 v118, v73
	v_mov_b32_e32 v119, v72
	v_mov_b32_e32 v72, v75
	v_mov_b32_e32 v73, v74
	v_pk_mul_f32 v[74:75], v[84:85], v[76:77] op_sel_hi:[0,1]
	v_pk_mul_f32 v[76:77], v[84:85], v[118:119] op_sel_hi:[0,1]
	v_pk_mul_f32 v[72:73], v[84:85], v[72:73] op_sel_hi:[0,1]
	v_pk_mul_f32 v[76:77], v[76:77], v[94:95]
	v_pk_mul_f32 v[74:75], v[74:75], v[96:97]
	v_pk_add_f32 v[94:95], v[100:101], 1.0 op_sel_hi:[1,0]
	v_pk_add_f32 v[96:97], v[98:99], 1.0 op_sel_hi:[1,0]
	v_pk_mul_f32 v[72:73], v[72:73], v[102:103]
	v_pk_mul_f32 v[78:79], v[78:79], v[104:105]
	v_pk_add_f32 v[98:99], v[108:109], 1.0 op_sel_hi:[1,0]
	v_pk_add_f32 v[100:101], v[106:107], 1.0 op_sel_hi:[1,0]
	v_pk_fma_f32 v[74:75], v[74:75], v[94:95], v[112:113]
	v_pk_fma_f32 v[76:77], v[76:77], v[96:97], v[110:111]
	v_pk_fma_f32 v[78:79], v[78:79], v[98:99], v[116:117]
	v_pk_fma_f32 v[72:73], v[72:73], v[100:101], v[114:115]
	v_bfe_u32 v25, v76, 16, 1
	v_bfe_u32 v29, v74, 16, 1
	v_bfe_u32 v33, v72, 16, 1
	v_bfe_u32 v37, v78, 16, 1
	v_bfe_u32 v27, v77, 16, 1
	v_bfe_u32 v31, v75, 16, 1
	v_bfe_u32 v35, v73, 16, 1
	v_bfe_u32 v39, v79, 16, 1
	v_add3_u32 v25, v76, v25, s27
	v_add3_u32 v29, v74, v29, s27
	v_add3_u32 v33, v72, v33, s27
	v_add3_u32 v37, v78, v37, s27
	v_add3_u32 v27, v77, v27, s27
	v_add3_u32 v31, v75, v31, s27
	v_add3_u32 v35, v73, v35, s27
	v_add3_u32 v39, v79, v39, s27
	v_lshrrev_b32_e32 v25, 16, v25
	v_lshrrev_b32_e32 v29, 16, v29
	v_lshrrev_b32_e32 v33, 16, v33
	v_lshrrev_b32_e32 v37, 16, v37
	v_and_or_b32 v72, v27, s25, v25
	v_and_or_b32 v73, v31, s25, v29
	v_and_or_b32 v74, v35, s25, v33
	v_and_or_b32 v75, v39, s25, v37
	global_store_dwordx4 v[82:83], v[72:75], off offset:3072
	s_nop 1
	v_mov_b64_e32 v[74:75], v[140:141]
	v_mov_b64_e32 v[76:77], v[142:143]
	s_nop 0
	s_nop 1
	v_mov_b64_e32 v[94:95], v[132:133]
	v_mov_b64_e32 v[96:97], v[134:135]
	v_mov_b64_e32 v[98:99], v[136:137]
	v_mov_b64_e32 v[100:101], v[138:139]
	v_mov_b64_e32 v[102:103], v[128:129]
	v_mov_b64_e32 v[104:105], v[130:131]
	v_mov_b64_e32 v[106:107], v[148:149]
	v_mov_b64_e32 v[108:109], v[150:151]
	v_mov_b64_e32 v[110:111], v[144:145]
	v_mov_b64_e32 v[112:113], v[146:147]
	v_mul_f32_e32 v25, 0x4b800000, v80
	v_cndmask_b32_e32 v25, v80, v25, vcc
	v_rsq_f32_e32 v25, v25
	v_lshl_add_u64 v[72:73], v[16:17], 0, s[8:9]
	s_cselect_b64 s[8:9], -1, 0
	v_mul_f32_e32 v27, 0x45800000, v25
	v_cndmask_b32_e32 v60, v25, v27, vcc
	v_pk_mul_f32 v[62:63], v[60:61], v[66:67] op_sel_hi:[0,1]
	v_pk_mul_f32 v[56:57], v[60:61], v[56:57] op_sel_hi:[0,1]
	v_pk_mul_f32 v[64:65], v[60:61], v[64:65] op_sel_hi:[0,1]
	v_pk_mul_f32 v[58:59], v[60:61], v[58:59] op_sel_hi:[0,1]
	v_pk_mul_f32 v[46:47], v[60:61], v[46:47] op_sel_hi:[0,1]
	v_pk_mul_f32 v[2:3], v[60:61], v[2:3] op_sel_hi:[0,1]
	v_pk_mul_f32 v[4:5], v[60:61], v[4:5] op_sel_hi:[0,1]
	v_pk_add_f32 v[66:67], v[96:97], 1.0 op_sel_hi:[1,0]
	v_pk_mul_f32 v[56:57], v[74:75], v[56:57]
	v_pk_mul_f32 v[62:63], v[76:77], v[62:63]
	v_pk_add_f32 v[68:69], v[94:95], 1.0 op_sel_hi:[1,0]
	v_pk_mul_f32 v[58:59], v[98:99], v[58:59]
	v_pk_mul_f32 v[64:65], v[100:101], v[64:65]
	v_pk_add_f32 v[70:71], v[104:105], 1.0 op_sel_hi:[1,0]
	v_pk_add_f32 v[74:75], v[102:103], 1.0 op_sel_hi:[1,0]
	v_pk_fma_f32 v[62:63], v[66:67], v[62:63], v[108:109]
	v_pk_fma_f32 v[56:57], v[68:69], v[56:57], v[106:107]
	v_pk_fma_f32 v[64:65], v[70:71], v[64:65], v[112:113]
	v_pk_fma_f32 v[58:59], v[74:75], v[58:59], v[110:111]
	v_bfe_u32 v25, v56, 16, 1
	v_bfe_u32 v29, v62, 16, 1
	v_bfe_u32 v33, v58, 16, 1
	v_bfe_u32 v37, v64, 16, 1
	v_bfe_u32 v27, v57, 16, 1
	v_bfe_u32 v31, v63, 16, 1
	v_bfe_u32 v35, v59, 16, 1
	v_bfe_u32 v39, v65, 16, 1
	v_add3_u32 v25, v56, v25, s27
	v_add3_u32 v29, v62, v29, s27
	v_add3_u32 v33, v58, v33, s27
	v_add3_u32 v37, v64, v37, s27
	v_add3_u32 v27, v57, v27, s27
	v_add3_u32 v31, v63, v31, s27
	v_add3_u32 v35, v59, v35, s27
	v_add3_u32 v39, v65, v39, s27
	v_lshrrev_b32_e32 v25, 16, v25
	v_lshrrev_b32_e32 v29, 16, v29
	v_lshrrev_b32_e32 v33, 16, v33
	v_lshrrev_b32_e32 v37, 16, v37
	v_and_or_b32 v56, v27, s25, v25
	v_and_or_b32 v57, v31, s25, v29
	v_and_or_b32 v58, v35, s25, v33
	v_and_or_b32 v59, v39, s25, v37
	global_store_dwordx4 v[72:73], v[56:59], off
	s_nop 1
	v_mov_b64_e32 v[56:57], v[152:153]
	v_mov_b64_e32 v[58:59], v[154:155]
	s_nop 0
	s_nop 1
	v_mov_b64_e32 v[62:63], v[156:157]
	v_mov_b64_e32 v[64:65], v[158:159]
	v_mov_b64_e32 v[66:67], v[164:165]
	v_mov_b64_e32 v[68:69], v[166:167]
	v_mov_b64_e32 v[74:75], v[168:169]
	v_mov_b64_e32 v[76:77], v[170:171]
	v_mov_b64_e32 v[78:79], v[160:161]
	v_mov_b64_e32 v[80:81], v[162:163]
	v_mov_b64_e32 v[94:95], v[172:173]
	v_mov_b64_e32 v[96:97], v[174:175]
	v_pk_mul_f32 v[28:29], v[60:61], v[48:49] op_sel_hi:[0,1]
	v_pk_mul_f32 v[32:33], v[60:61], v[44:45] op_sel_hi:[0,1]
	v_pk_mul_f32 v[44:45], v[60:61], v[52:53] op_sel_hi:[0,1]
	v_pk_mul_f32 v[32:33], v[56:57], v[32:33]
	v_pk_mul_f32 v[28:29], v[58:59], v[28:29]
	v_pk_add_f32 v[48:49], v[64:65], 1.0 op_sel_hi:[1,0]
; __device__ __forceinline__ unsigned pk2(float lo, float hi) { return f2bf(lo) | (f2bf(hi) << 16); }
; template <bool ZP, bool XF32, bool OUT8 = false>
; __device__ __forceinline__ void norm_phase(LAS unsigned char* lds, const void* xin, const float* gain, const float* sh, const float* sc, bf16* hout, const float* wzt, float* zout, int lane, int wave, int vcu, int G) {
;     ...
;         for (int r = 0; r < 2; ++r) { const int m = m0 + r, b = m >> 11;
;             const float rstd = rsqrtf(wave_sum(ss[r]) * (1.0f / D) + EPS);
; #pragma unroll
;             for (int j = 0; j < 4; ++j) { const int col = 512 * j + 8 * lane;
; #pragma unroll
;                 for (int q = 0; q < 2; ++q) { const f32x4 gg = *(const f32x4*)(gain + col + 4 * q), s1 = *(const f32x4*)(sc + (size_t)b * MODW + col + 4 * q), s0 = *(const f32x4*)(sh + (size_t)b * MODW + col + 4 * q);
;                     v[r][j][q] = (v[r][j][q] * rstd * gg) * (s1 + 1.0f) + s0; }
;                 if constexpr (OUT8) { *(v2u*)((unsigned char*)hout + (size_t)m * D + col) = pack8_fp8(v[r][j][0][0], v[r][j][0][1], v[r][j][0][2], v[r][j][0][3], v[r][j][1][0], v[r][j][1][1], v[r][j][1][2], v[r][j][1][3], FP8_ASCALE); }
;                 else { v4u o; o.x = pk2(v[r][j][0][0], v[r][j][0][1]); o.y = pk2(v[r][j][0][2], v[r][j][0][3]); o.z = pk2(v[r][j][1][0], v[r][j][1][1]); o.w = pk2(v[r][j][1][2], v[r][j][1][3]);
;                     *(v4u*)(hout + (size_t)m * D + col) = o; } }
	v_pk_add_f32 v[50:51], v[62:63], 1.0 op_sel_hi:[1,0]
	v_pk_mul_f32 v[46:47], v[66:67], v[46:47]
	v_pk_mul_f32 v[44:45], v[68:69], v[44:45]
	v_pk_add_f32 v[52:53], v[76:77], 1.0 op_sel_hi:[1,0]
	v_pk_add_f32 v[54:55], v[74:75], 1.0 op_sel_hi:[1,0]
	v_pk_fma_f32 v[28:29], v[48:49], v[28:29], v[80:81]
	v_pk_fma_f32 v[32:33], v[50:51], v[32:33], v[78:79]
	v_pk_fma_f32 v[44:45], v[52:53], v[44:45], v[96:97]
	v_pk_fma_f32 v[46:47], v[54:55], v[46:47], v[94:95]
	v_bfe_u32 v25, v32, 16, 1
	v_bfe_u32 v27, v33, 16, 1
	v_bfe_u32 v31, v28, 16, 1
	v_bfe_u32 v37, v46, 16, 1
	v_bfe_u32 v41, v44, 16, 1
	v_bfe_u32 v35, v29, 16, 1
	v_bfe_u32 v39, v47, 16, 1
	v_bfe_u32 v43, v45, 16, 1
	v_add3_u32 v25, v32, v25, s27
	v_add3_u32 v27, v33, v27, s27
	v_add3_u32 v28, v28, v31, s27
	v_add3_u32 v31, v46, v37, s27
	v_add3_u32 v33, v44, v41, s27
	v_add3_u32 v29, v29, v35, s27
	v_add3_u32 v32, v47, v39, s27
	v_add3_u32 v35, v45, v43, s27
	v_lshrrev_b32_e32 v25, 16, v25
	v_lshrrev_b32_e32 v28, 16, v28
	v_lshrrev_b32_e32 v31, 16, v31
	v_lshrrev_b32_e32 v33, 16, v33
	v_and_or_b32 v44, v27, s25, v25
	v_and_or_b32 v45, v29, s25, v28
	v_and_or_b32 v46, v32, s25, v31
	v_and_or_b32 v47, v35, s25, v33
	global_store_dwordx4 v[72:73], v[44:47], off offset:1024
	s_nop 1
	v_mov_b64_e32 v[44:45], v[176:177]
	v_mov_b64_e32 v[46:47], v[178:179]
	s_nop 0
	s_nop 1
	v_mov_b64_e32 v[48:49], v[180:181]
	v_mov_b64_e32 v[50:51], v[182:183]
	v_mov_b64_e32 v[52:53], v[184:185]
	v_mov_b64_e32 v[54:55], v[186:187]
	v_mov_b64_e32 v[56:57], v[188:189]
	v_mov_b64_e32 v[58:59], v[190:191]
	v_mov_b64_e32 v[62:63], v[192:193]
	v_mov_b64_e32 v[64:65], v[194:195]
	v_mov_b64_e32 v[66:67], v[196:197]
	v_mov_b64_e32 v[68:69], v[198:199]
	v_mov_b32_e32 v41, v42
	v_mov_b32_e32 v37, v38
	v_mov_b32_e32 v31, v34
	v_mov_b32_e32 v25, v26
	v_pk_mul_f32 v[26:27], v[60:61], v[30:31] op_sel_hi:[0,1]
	v_pk_mul_f32 v[24:25], v[60:61], v[24:25] op_sel_hi:[0,1]
	v_pk_mul_f32 v[28:29], v[60:61], v[40:41] op_sel_hi:[0,1]
	v_pk_mul_f32 v[30:31], v[60:61], v[36:37] op_sel_hi:[0,1]
	v_pk_mul_f32 v[24:25], v[24:25], v[44:45]
	v_pk_mul_f32 v[26:27], v[26:27], v[46:47]
	v_pk_add_f32 v[32:33], v[50:51], 1.0 op_sel_hi:[1,0]
	v_pk_add_f32 v[34:35], v[48:49], 1.0 op_sel_hi:[1,0]
	v_pk_mul_f32 v[30:31], v[30:31], v[52:53]
	v_pk_mul_f32 v[28:29], v[28:29], v[54:55]
	v_pk_add_f32 v[36:37], v[58:59], 1.0 op_sel_hi:[1,0]
	v_pk_add_f32 v[38:39], v[56:57], 1.0 op_sel_hi:[1,0]
	v_pk_fma_f32 v[26:27], v[26:27], v[32:33], v[64:65]
	v_pk_fma_f32 v[24:25], v[24:25], v[34:35], v[62:63]
	v_pk_fma_f32 v[28:29], v[28:29], v[36:37], v[68:69]
	v_pk_fma_f32 v[30:31], v[30:31], v[38:39], v[66:67]
	v_bfe_u32 v32, v24, 16, 1
	v_bfe_u32 v34, v26, 16, 1
	v_bfe_u32 v36, v30, 16, 1
	v_bfe_u32 v38, v28, 16, 1
	v_bfe_u32 v33, v25, 16, 1
	v_bfe_u32 v35, v27, 16, 1
	v_bfe_u32 v37, v31, 16, 1
	v_bfe_u32 v39, v29, 16, 1
	v_add3_u32 v24, v24, v32, s27
	v_add3_u32 v26, v26, v34, s27
	v_add3_u32 v30, v30, v36, s27
	v_add3_u32 v28, v28, v38, s27
	v_add3_u32 v25, v25, v33, s27
	v_add3_u32 v27, v27, v35, s27
	v_add3_u32 v31, v31, v37, s27
	v_add3_u32 v29, v29, v39, s27
	v_lshrrev_b32_e32 v24, 16, v24
	v_lshrrev_b32_e32 v26, 16, v26
	v_lshrrev_b32_e32 v30, 16, v30
	v_lshrrev_b32_e32 v28, 16, v28
	v_and_or_b32 v24, v25, s25, v24
	v_and_or_b32 v25, v27, s25, v26
	v_and_or_b32 v26, v31, s25, v30
	v_and_or_b32 v27, v29, s25, v28
	global_store_dwordx4 v[72:73], v[24:27], off offset:2048
	s_nop 1
	v_mov_b64_e32 v[24:25], v[200:201]
	v_mov_b64_e32 v[26:27], v[202:203]
	s_nop 0
	s_nop 1
	v_mov_b64_e32 v[28:29], v[204:205]
	v_mov_b64_e32 v[30:31], v[206:207]
	v_mov_b64_e32 v[32:33], v[208:209]
	v_mov_b64_e32 v[34:35], v[210:211]
	v_mov_b64_e32 v[36:37], v[212:213]
	v_mov_b64_e32 v[38:39], v[214:215]
	v_mov_b64_e32 v[40:41], v[216:217]
	v_mov_b64_e32 v[42:43], v[218:219]
	v_mov_b64_e32 v[44:45], v[220:221]
	v_mov_b64_e32 v[46:47], v[222:223]
	v_mov_b32_e32 v48, v23
	v_mov_b32_e32 v49, v22
	v_mov_b32_e32 v22, v21
	v_mov_b32_e32 v23, v20
	v_pk_mul_f32 v[20:21], v[60:61], v[48:49] op_sel_hi:[0,1]
	v_pk_mul_f32 v[22:23], v[60:61], v[22:23] op_sel_hi:[0,1]
	v_pk_mul_f32 v[20:21], v[20:21], v[24:25]
	v_pk_mul_f32 v[2:3], v[2:3], v[26:27]
	v_pk_add_f32 v[24:25], v[30:31], 1.0 op_sel_hi:[1,0]
	v_pk_add_f32 v[26:27], v[28:29], 1.0 op_sel_hi:[1,0]
	v_pk_mul_f32 v[22:23], v[22:23], v[32:33]
	v_pk_mul_f32 v[4:5], v[4:5], v[34:35]
	v_pk_add_f32 v[28:29], v[38:39], 1.0 op_sel_hi:[1,0]
	v_pk_add_f32 v[30:31], v[36:37], 1.0 op_sel_hi:[1,0]
	v_pk_fma_f32 v[2:3], v[2:3], v[24:25], v[42:43]
	v_pk_fma_f32 v[20:21], v[20:21], v[26:27], v[40:41]
	v_pk_fma_f32 v[4:5], v[4:5], v[28:29], v[46:47]
	v_pk_fma_f32 v[22:23], v[22:23], v[30:31], v[44:45]
	v_bfe_u32 v24, v20, 16, 1
	v_bfe_u32 v26, v2, 16, 1
	v_bfe_u32 v28, v22, 16, 1
	v_bfe_u32 v30, v4, 16, 1
	v_bfe_u32 v25, v21, 16, 1
	v_bfe_u32 v27, v3, 16, 1
	v_bfe_u32 v29, v23, 16, 1
	v_bfe_u32 v31, v5, 16, 1
	v_add3_u32 v20, v20, v24, s27
	v_add3_u32 v2, v2, v26, s27
	v_add3_u32 v22, v22, v28, s27
	v_add3_u32 v4, v4, v30, s27
	v_add3_u32 v21, v21, v25, s27
	v_add3_u32 v3, v3, v27, s27
	v_add3_u32 v23, v23, v29, s27
	v_add3_u32 v5, v5, v31, s27
	v_lshrrev_b32_e32 v20, 16, v20
	v_lshrrev_b32_e32 v24, 16, v2
	v_lshrrev_b32_e32 v22, 16, v22
	v_lshrrev_b32_e32 v25, 16, v4
	v_and_or_b32 v2, v21, s25, v20
	v_and_or_b32 v3, v3, s25, v24
	v_and_or_b32 v4, v23, s25, v22
	v_and_or_b32 v5, v5, s25, v25
	global_store_dwordx4 v[72:73], v[2:5], off offset:3072
	s_branch .LBB0_936
